# lp=1 block order changed for cache locality: prep (ssd/gla) -> intra-chunk tail -> prep_dn_chunk -> DeltaNet D1 (consumers run right after their producers)
# speedup vs baseline: 1.0395x; 1.0067x over previous
; __device__ void prep_ssd(const Ctx& c, int ck, int blk) {
;     const bf16_t* proj = c.W<bf16_t>(WS_PROJ);
;     const float* cw = c.in(I_SCONVW) + (size_t)c.layer * 4 * 1536; const float* cb = c.in(I_SCONVB) + (size_t)c.layer * 1536;
;     const int tid = c.tid, t0 = ck * 64;
;     float* dt_s = c.ldsf; float* acs_s = c.ldsf + 512;
;     __syncthreads();
;     if (blk < 2) {
;         { const int hh = tid >> 6, l = tid & 63, h = blk * 8 + hh;
;           const float raw = bf2f(proj[(size_t)(t0 + l) * NP + C_SDT + h]);
;           const float dt = softplusf_(raw + c.in(I_SDTB)[c.layer * 16 + h]);
;           float a = dt * (-__expf(c.in(I_SALOG)[c.layer * 16 + h]));
; #pragma unroll
;           for (int d = 1; d < 64; d <<= 1) { const float o = __shfl_up(a, d); if (l >= d) a += o; }
;           dt_s[tid] = dt; acs_s[tid] = a; }
;         __syncthreads();
;         { const int h = blk * 8 + (tid >> 6); c.W<float>(WS_SACS)[(size_t)(ck * 16 + h) * 64 + (tid & 63)] = acs_s[tid]; }
;         const int ch = blk * 512 + tid, h = ch >> 6, p = ch & 63, hh = tid >> 6;
;         const float w0 = cw[ch], w1 = cw[1536 + ch], w2 = cw[2 * 1536 + ch], w3 = cw[3 * 1536 + ch], bb = cb[ch];
;         float xm3 = 0.f, xm2 = 0.f, xm1 = 0.f;
;         if (t0 > 0) { xm3 = bf2f(proj[(size_t)(t0 - 3) * NP + C_SX + ch]); xm2 = bf2f(proj[(size_t)(t0 - 2) * NP + C_SX + ch]); xm1 = bf2f(proj[(size_t)(t0 - 1) * NP + C_SX + ch]); }
;         const float acl = acs_s[hh * 64 + 63];
;         bf16_t* sX = c.W<bf16_t>(WS_SX); bf16_t* sXdT = c.W<bf16_t>(WS_SXDT); bf16_t* sXwT = c.W<bf16_t>(WS_SXW);
;         float raw[64];
;         { unsigned rw[64];
; #pragma unroll
;           for (int l = 0; l < 64; ++l) rw[l] = proj[(size_t)(t0 + l) * NP + C_SX + ch];
;           PIN16(rw, 0); PIN16(rw, 16); PIN16(rw, 32); PIN16(rw, 48);
; #pragma unroll
;           for (int l = 0; l < 64; ++l) raw[l] = __uint_as_float(rw[l] << 16); }
; #pragma unroll
;         for (int l0 = 0; l0 < 64; l0 += 8) {
;             float xd[8], xw[8];
; #pragma unroll
;             for (int j = 0; j < 8; ++j) { const int l = l0 + j;
;                 const float xc = raw[l];
;                 const float y = w0 * xm3 + w1 * xm2 + w2 * xm1 + w3 * xc + bb; xm3 = xm2; xm2 = xm1; xm1 = xc;
;                 const float x = siluf_(y);
;                 sX[(size_t)(t0 + l) * 1024 + ch] = f2bf(x);
.LBB0_609:
	v_writelane_b32 v248, s28, 35
	v_writelane_b32 v248, s29, 36
	v_writelane_b32 v248, s30, 37
	v_writelane_b32 v248, s31, 38
	s_waitcnt vmcnt(0)
.Lprep_entry:
	s_mov_b64 exec, -1
	v_readlane_b32 s0, v247, 1
	v_readlane_b32 s1, v247, 2
	v_readlane_b32 s6, v247, 0
	v_readlane_b32 s16, v248, 25
	v_readfirstlane_b32 s9, v234
	s_load_dwordx2 s[4:5], s[0:1], 0xe8
	s_lshr_b32 s16, s16, 3
	s_lshr_b32 s9, s9, 6
	s_lshr_b32 s7, s6, 1
	s_and_b32 s8, s6, 1
	s_lshl_b32 s15, s7, 6
	v_and_b32_e32 v3, 63, v234
	s_mov_b32 s18, 0xbfb8aa3b
	s_mov_b32 s19, 0xbfb8aa3b
	s_mov_b32 s28, 0xbfb8aa3b
	s_mov_b32 s36, 1.0
	s_mov_b32 s37, 1.0
	s_lshl_b32 s17, s9, 3
	s_add_u32 s17, s17, s15
	s_add_i32 s10, s17, -3
	s_waitcnt lgkmcnt(0)
	s_mul_i32 s22, s10, 0x7e00
	s_ashr_i32 s23, s22, 31
	s_add_u32 s38, s4, s22
	s_addc_u32 s39, s5, s23
	s_add_u32 s38, s38, 0x9c00000
	s_addc_u32 s39, s39, 0
	s_lshl_b32 s13, s8, 3
	s_add_u32 s13, s13, s9
	v_add_u32_e32 v12, s15, v3
	s_mov_b32 s25, 0x7e00
	v_mul_lo_u32 v12, v12, s25
	s_lshl_b32 s22, s13, 1
	v_add_u32_e32 v12, s22, v12
	v_add_u32_e32 v12, 0x9c03420, v12
	global_load_ushort v13, v12, s[4:5]
	s_load_dwordx2 s[32:33], s[0:1], 0x50
	s_load_dwordx2 s[34:35], s[0:1], 0x58
	s_lshl_b32 s22, s16, 4
	s_add_u32 s22, s22, s13
	s_lshl_b32 s22, s22, 2
	s_waitcnt lgkmcnt(0)
	s_load_dword s26, s[32:33], s22
	s_load_dword s27, s[34:35], s22
	v_lshlrev_b32_e32 v0, 3, v3
	s_lshl_b32 s22, s8, 9
	v_add_u32_e32 v0, s22, v0
	v_lshlrev_b32_e32 v1, 2, v0
	v_lshlrev_b32_e32 v0, 1, v0
	v_add_u32_e32 v2, 0x29901000, v0
	v_add_u32_e32 v0, 0x2820, v0
	s_mov_b64 s[100:101], s[38:39]
	global_load_dwordx4 v[16:19], v0, s[100:101]
	s_add_u32 s100, s100, 0x7e00
	s_addc_u32 s101, s101, 0
	global_load_dwordx4 v[20:23], v0, s[100:101]
	s_add_u32 s100, s100, 0x7e00
	s_addc_u32 s101, s101, 0
	global_load_dwordx4 v[24:27], v0, s[100:101]
	s_add_u32 s100, s100, 0x7e00
	s_addc_u32 s101, s101, 0
	global_load_dwordx4 v[28:31], v0, s[100:101]
	s_add_u32 s100, s100, 0x7e00
	s_addc_u32 s101, s101, 0
	global_load_dwordx4 v[32:35], v0, s[100:101]
	s_add_u32 s100, s100, 0x7e00
	s_addc_u32 s101, s101, 0
	global_load_dwordx4 v[36:39], v0, s[100:101]
	s_add_u32 s100, s100, 0x7e00
	s_addc_u32 s101, s101, 0
	global_load_dwordx4 v[40:43], v0, s[100:101]
	s_add_u32 s100, s100, 0x7e00
	s_addc_u32 s101, s101, 0
	global_load_dwordx4 v[44:47], v0, s[100:101]
	s_add_u32 s100, s100, 0x7e00
	s_addc_u32 s101, s101, 0
	global_load_dwordx4 v[48:51], v0, s[100:101]
	s_add_u32 s100, s100, 0x7e00
	s_addc_u32 s101, s101, 0
	global_load_dwordx4 v[52:55], v0, s[100:101]
	s_add_u32 s100, s100, 0x7e00
	s_addc_u32 s101, s101, 0
	global_load_dwordx4 v[56:59], v0, s[100:101]
	s_load_dwordx2 s[40:41], s[0:1], 0x40
	s_load_dwordx2 s[42:43], s[0:1], 0x48
	s_mul_i32 s22, s16, 0x6000
	s_mul_i32 s23, s16, 0x1800
	s_waitcnt lgkmcnt(0)
	s_add_u32 s40, s40, s22
	s_addc_u32 s41, s41, 0
	s_add_u32 s42, s42, s23
	s_addc_u32 s43, s43, 0
	global_load_dwordx4 v[60:63], v1, s[40:41] offset:0
	global_load_dwordx4 v[64:67], v1, s[40:41] offset:16
	s_add_u32 s40, s40, 0x1800
	s_addc_u32 s41, s41, 0
	global_load_dwordx4 v[68:71], v1, s[40:41] offset:0
	global_load_dwordx4 v[72:75], v1, s[40:41] offset:16
	s_add_u32 s40, s40, 0x1800
	s_addc_u32 s41, s41, 0
	global_load_dwordx4 v[76:79], v1, s[40:41] offset:0
	global_load_dwordx4 v[80:83], v1, s[40:41] offset:16
	s_add_u32 s40, s40, 0x1800
	s_addc_u32 s41, s41, 0
	global_load_dwordx4 v[84:87], v1, s[40:41] offset:0
	global_load_dwordx4 v[88:91], v1, s[40:41] offset:16
	global_load_dwordx4 v[92:95], v1, s[42:43] offset:0
	global_load_dwordx4 v[96:99], v1, s[42:43] offset:16
	s_waitcnt vmcnt(21) lgkmcnt(0)
	v_lshlrev_b32_e32 v13, 16, v13
	v_add_f32_e32 v14, s26, v13
	v_mul_f32_e64 v15, |v14|, s28
	v_exp_f32_e32 v15, v15
	v_max_f32_e32 v14, 0, v14
	v_add_f32_e32 v15, 1.0, v15
	v_log_f32_e32 v15, v15
	s_nop 0
	v_fmac_f32_e32 v14, 0x3f317218, v15
	v_mov_b32_e32 v12, s27
	v_mul_f32_e32 v12, 0x3fb8aa3b, v12
	v_exp_f32_e32 v12, v12
	s_nop 0
	v_mul_f32_e64 v15, v14, -v12
	v_subrev_u32_e32 v12, 1, v3
	v_max_i32_e32 v12, 0, v12
	v_lshlrev_b32_e32 v12, 2, v12
	ds_bpermute_b32 v13, v12, v15
	v_cmp_le_u32_e32 vcc, 1, v3
	s_waitcnt lgkmcnt(0)
	v_add_f32_e32 v13, v15, v13
	v_cndmask_b32_e32 v15, v15, v13, vcc
	v_subrev_u32_e32 v12, 2, v3
	v_max_i32_e32 v12, 0, v12
	v_lshlrev_b32_e32 v12, 2, v12
	ds_bpermute_b32 v13, v12, v15
	v_cmp_le_u32_e32 vcc, 2, v3
	s_waitcnt lgkmcnt(0)
	v_add_f32_e32 v13, v15, v13
	v_cndmask_b32_e32 v15, v15, v13, vcc
	v_subrev_u32_e32 v12, 4, v3
	v_max_i32_e32 v12, 0, v12
	v_lshlrev_b32_e32 v12, 2, v12
	ds_bpermute_b32 v13, v12, v15
	v_cmp_le_u32_e32 vcc, 4, v3
	s_waitcnt lgkmcnt(0)
	v_add_f32_e32 v13, v15, v13
	v_cndmask_b32_e32 v15, v15, v13, vcc
	v_subrev_u32_e32 v12, 8, v3
	v_max_i32_e32 v12, 0, v12
	v_lshlrev_b32_e32 v12, 2, v12
	ds_bpermute_b32 v13, v12, v15
	v_cmp_le_u32_e32 vcc, 8, v3
	s_waitcnt lgkmcnt(0)
	v_add_f32_e32 v13, v15, v13
	v_cndmask_b32_e32 v15, v15, v13, vcc
	v_subrev_u32_e32 v12, 16, v3
	v_max_i32_e32 v12, 0, v12
	v_lshlrev_b32_e32 v12, 2, v12
	ds_bpermute_b32 v13, v12, v15
	v_cmp_le_u32_e32 vcc, 16, v3
	s_waitcnt lgkmcnt(0)
	v_add_f32_e32 v13, v15, v13
	v_cndmask_b32_e32 v15, v15, v13, vcc
	v_subrev_u32_e32 v12, 32, v3
	v_max_i32_e32 v12, 0, v12
	v_lshlrev_b32_e32 v12, 2, v12
	ds_bpermute_b32 v13, v12, v15
	v_cmp_le_u32_e32 vcc, 32, v3
	s_waitcnt lgkmcnt(0)
	v_add_f32_e32 v13, v15, v13
	v_cndmask_b32_e32 v15, v15, v13, vcc
	s_nop 1
	v_readlane_b32 s29, v15, 63
	v_lshlrev_b32_e32 v12, 2, v3
	s_lshl_b32 s22, s9, 8
	v_add_u32_e32 v12, s22, v12
	ds_write_b32 v12, v14 offset:0
	v_sub_f32_e32 v13, s29, v15
	v_mul_f32_e32 v13, 0x3fb8aa3b, v13
	v_exp_f32_e32 v13, v13
	s_lshl_b32 s22, s7, 4
	s_add_u32 s22, s22, s13
	s_lshl_b32 s22, s22, 8
	v_lshl_add_u32 v14, v3, 2, s22
	v_add_u32_e32 v14, 0x30501000, v14
	global_store_dword v14, v15, s[4:5]
	ds_write_b32 v12, v13 offset:2048
	s_waitcnt lgkmcnt(0)
	s_barrier
	v_lshrrev_b32_e32 v6, 3, v3
	v_lshlrev_b32_e32 v6, 8, v6
	s_lshl_b32 s22, s9, 5
	v_add_u32_e32 v6, s22, v6
	ds_read_b128 v[224:227], v6 offset:0
	ds_read_b128 v[228:231], v6 offset:16
	ds_read_b128 v[8:11], v6 offset:2048
	ds_read_b128 v[12:15], v6 offset:2064
	s_lshl_b32 s22, s7, 4
	s_lshl_b32 s23, s8, 3
	s_add_u32 s22, s22, s23
	s_lshl_b32 s22, s22, 13
	v_lshl_add_u32 v4, v3, 10, s22
	s_lshl_b32 s23, s9, 4
	v_add_u32_e32 v4, s23, v4
	v_add_u32_e32 v5, 0x2b901000, v4
	v_add_u32_e32 v4, 0x2a901000, v4
	s_lshl_b32 s22, s17, 11
	s_add_u32 s44, s4, s22
	s_addc_u32 s45, s5, 0
	s_waitcnt vmcnt(0) lgkmcnt(0)
	s_cmp_lt_i32 s10, 0
	s_cbranch_scc0 .Lprep_nz_ssda
	v_mov_b32_e32 v16, 0
	v_mov_b32_e32 v17, 0
	v_mov_b32_e32 v18, 0
	v_mov_b32_e32 v19, 0
	v_mov_b32_e32 v20, 0
	v_mov_b32_e32 v21, 0
	v_mov_b32_e32 v22, 0
	v_mov_b32_e32 v23, 0
	v_mov_b32_e32 v24, 0
	v_mov_b32_e32 v25, 0
	v_mov_b32_e32 v26, 0
	v_mov_b32_e32 v27, 0

; __device__ __forceinline__ f32x4 mfma16(bf16x8 a, bf16x8 b, f32x4 c) { return __builtin_amdgcn_mfma_f32_16x16x32_bf16(a, b, c, 0, 0, 0); }
; #define PIN16(a, o) asm volatile("" : "+v"(a[(o)+0]), "+v"(a[(o)+1]), "+v"(a[(o)+2]), "+v"(a[(o)+3]), "+v"(a[(o)+4]), "+v"(a[(o)+5]), "+v"(a[(o)+6]), "+v"(a[(o)+7]), \
;     "+v"(a[(o)+8]), "+v"(a[(o)+9]), "+v"(a[(o)+10]), "+v"(a[(o)+11]), "+v"(a[(o)+12]), "+v"(a[(o)+13]), "+v"(a[(o)+14]), "+v"(a[(o)+15]))
;     template <class Tp> __device__ __forceinline__ Tp* W(size_t off) const { return (Tp*)(ws + off); }
; __device__ void prep_gla(const Ctx& c, int ck, int blk) {
;     ...
;         const int ch = (blk - 1) * 512 + tid, h = ch >> 8, v = ch & 255;
;         bf16_t* gVT = c.W<bf16_t>(WS_GVT);
;         unsigned e[64];
; #pragma unroll
;         for (int l = 0; l < 64; ++l) e[l] = proj[(size_t)(t0 + l) * NP + C_GV + ch];
;         PIN16(e, 0); PIN16(e, 16); PIN16(e, 32); PIN16(e, 48);
; #pragma unroll
;         for (int l0 = 0; l0 < 64; l0 += 8) {
;             u32x4 a; a.x = e[l0] | (e[l0 + 1] << 16); a.y = e[l0 + 2] | (e[l0 + 3] << 16); a.z = e[l0 + 4] | (e[l0 + 5] << 16); a.w = e[l0 + 6] | (e[l0 + 7] << 16);
;             *(u32x4*)(gVT + ((size_t)(ck * 4 + h) * 256 + v) * 64 + l0) = a;
;         }
; __device__ void ssd_mm(const Ctx& c, int ck, int g, int lb) {
;     const bf16_t* sB = c.W<bf16_t>(WS_SB); const bf16_t* sC = c.W<bf16_t>(WS_SC); const float* sAcs = c.W<float>(WS_SACS); bf16_t* sMm = c.W<bf16_t>(WS_SMM);
;     const int r = c.r, q = c.q, t0 = ck * 64;
;     f32x4 cb[4];
; #pragma unroll
;     for (int sb = 0; sb < 4; ++sb) { f32x4 a = (f32x4){0.f, 0.f, 0.f, 0.f};
; #pragma unroll
;         for (int k0 = 0; k0 < 128; k0 += 32)
;             a = mfma16(ldfrag(sB + (size_t)(t0 + sb * 16 + r) * 256 + g * 128 + k0 + q * 8), ldfrag(sC + (size_t)(t0 + lb * 16 + r) * 256 + g * 128 + k0 + q * 8), a);
;         cb[sb] = a; }
.Lprep_gdec_done:
	v_lshlrev_b32_e32 v12, 3, v3
	s_lshl_b32 s22, s8, 9
	v_add_u32_e32 v12, s22, v12
	v_lshlrev_b32_e32 v0, 1, v12
	v_add_u32_e32 v0, 0x3c40, v0
	s_lshl_b32 s22, s7, 10
	v_add_u32_e32 v1, s22, v12
	v_lshlrev_b32_e32 v1, 7, v1
	s_lshl_b32 s23, s9, 4
	v_add_u32_e32 v1, s23, v1
	v_add_u32_e32 v1, 0x31d81000, v1
	s_add_u32 s100, s38, 0x17a00
	s_addc_u32 s101, s39, 0
	global_load_dwordx4 v[16:19], v0, s[100:101]
	s_add_u32 s100, s100, 0x7e00
	s_addc_u32 s101, s101, 0
	global_load_dwordx4 v[20:23], v0, s[100:101]
	s_add_u32 s100, s100, 0x7e00
	s_addc_u32 s101, s101, 0
	global_load_dwordx4 v[24:27], v0, s[100:101]
	s_add_u32 s100, s100, 0x7e00
	s_addc_u32 s101, s101, 0
	global_load_dwordx4 v[28:31], v0, s[100:101]
	s_add_u32 s100, s100, 0x7e00
	s_addc_u32 s101, s101, 0
	global_load_dwordx4 v[32:35], v0, s[100:101]
	s_add_u32 s100, s100, 0x7e00
	s_addc_u32 s101, s101, 0
	global_load_dwordx4 v[36:39], v0, s[100:101]
	s_add_u32 s100, s100, 0x7e00
	s_addc_u32 s101, s101, 0
	global_load_dwordx4 v[40:43], v0, s[100:101]
	s_add_u32 s100, s100, 0x7e00
	s_addc_u32 s101, s101, 0
	global_load_dwordx4 v[44:47], v0, s[100:101]
	s_mov_b32 s22, 0x05040100
	s_mov_b32 s23, 0x07060302
	s_waitcnt vmcnt(0)
	v_perm_b32 v64, v20, v16, s22
	v_perm_b32 v65, v28, v24, s22
	v_perm_b32 v66, v36, v32, s22
	v_perm_b32 v67, v44, v40, s22
	global_store_dwordx4 v1, v[64:67], s[4:5] offset:0
	v_perm_b32 v68, v20, v16, s23
	v_perm_b32 v69, v28, v24, s23
	v_perm_b32 v70, v36, v32, s23
	v_perm_b32 v71, v44, v40, s23
	global_store_dwordx4 v1, v[68:71], s[4:5] offset:128
	v_perm_b32 v64, v21, v17, s22
	v_perm_b32 v65, v29, v25, s22
	v_perm_b32 v66, v37, v33, s22
	v_perm_b32 v67, v45, v41, s22
	global_store_dwordx4 v1, v[64:67], s[4:5] offset:256
	v_perm_b32 v68, v21, v17, s23
	v_perm_b32 v69, v29, v25, s23
	v_perm_b32 v70, v37, v33, s23
	v_perm_b32 v71, v45, v41, s23
	global_store_dwordx4 v1, v[68:71], s[4:5] offset:384
	v_perm_b32 v64, v22, v18, s22
	v_perm_b32 v65, v30, v26, s22
	v_perm_b32 v66, v38, v34, s22
	v_perm_b32 v67, v46, v42, s22
	global_store_dwordx4 v1, v[64:67], s[4:5] offset:512
	v_perm_b32 v68, v22, v18, s23
	v_perm_b32 v69, v30, v26, s23
	v_perm_b32 v70, v38, v34, s23
	v_perm_b32 v71, v46, v42, s23
	global_store_dwordx4 v1, v[68:71], s[4:5] offset:640
	v_perm_b32 v64, v23, v19, s22
	v_perm_b32 v65, v31, v27, s22
	v_perm_b32 v66, v39, v35, s22
	v_perm_b32 v67, v47, v43, s22
	global_store_dwordx4 v1, v[64:67], s[4:5] offset:768
	v_perm_b32 v68, v23, v19, s23
	v_perm_b32 v69, v31, v27, s23
	v_perm_b32 v70, v39, v35, s23
	v_perm_b32 v71, v47, v43, s23
	global_store_dwordx4 v1, v[68:71], s[4:5] offset:896
	s_waitcnt vmcnt(0) lgkmcnt(0)
	s_barrier
.Lmy_tail:
	s_mov_b64 exec, -1
	v_readlane_b32 s0, v247, 1
	v_readlane_b32 s1, v247, 2
	v_readlane_b32 s6, v247, 0
	v_readfirstlane_b32 s9, v234
	s_load_dwordx2 s[4:5], s[0:1], 0xe8
	v_and_b32_e32 v1, 15, v234
	v_bfe_u32 v2, v234, 4, 2
	s_lshr_b32 s9, s9, 6
	s_lshr_b32 s7, s6, 1
	s_and_b32 s8, s6, 1
	s_and_b32 s10, s9, 3
	s_lshr_b32 s11, s9, 2
	v_lshlrev_b32_e32 v3, 4, v2
	v_lshl_add_u32 v4, v1, 9, v3
	v_lshl_add_u32 v5, v1, 7, v3
	v_lshl_add_u32 v6, v1, 8, v3
	v_lshlrev_b32_e32 v7, 3, v2
	v_lshl_add_u32 v8, v1, 8, v7
	v_lshl_add_u32 v9, v1, 7, v7
	v_lshlrev_b32_e32 v10, 2, v1
	v_lshlrev_b32_e32 v11, 2, v2
	s_waitcnt lgkmcnt(0)
	s_add_u32 s12, s4, 0x2c901000
	s_addc_u32 s13, s5, 0
	s_lshl_b32 s3, s7, 15
	s_add_u32 s12, s12, s3
	s_addc_u32 s13, s13, 0
	s_lshl_b32 s3, s8, 8
	s_add_u32 s12, s12, s3
	s_addc_u32 s13, s13, 0
	s_add_u32 s14, s12, 0x2000
	s_addc_u32 s15, s13, 0
	s_add_u32 s16, s12, 0x4000
	s_addc_u32 s17, s13, 0
	s_add_u32 s18, s12, 0x6000
	s_addc_u32 s19, s13, 0
	s_add_u32 s20, s4, 0x2cd01000
	s_addc_u32 s21, s5, 0
	s_lshl_b32 s3, s7, 15
	s_add_u32 s20, s20, s3
	s_addc_u32 s21, s21, 0
	s_lshl_b32 s3, s10, 13
	s_add_u32 s20, s20, s3
	s_addc_u32 s21, s21, 0
	s_lshl_b32 s3, s8, 8
	s_add_u32 s20, s20, s3
	s_addc_u32 s21, s21, 0
	global_load_dwordx4 v[32:35], v4, s[12:13] offset:0
	global_load_dwordx4 v[36:39], v4, s[12:13] offset:64
	global_load_dwordx4 v[40:43], v4, s[12:13] offset:128
	global_load_dwordx4 v[44:47], v4, s[12:13] offset:192
	global_load_dwordx4 v[48:51], v4, s[14:15] offset:0
	global_load_dwordx4 v[52:55], v4, s[14:15] offset:64
	global_load_dwordx4 v[56:59], v4, s[14:15] offset:128
	global_load_dwordx4 v[60:63], v4, s[14:15] offset:192
	global_load_dwordx4 v[64:67], v4, s[16:17] offset:0
	global_load_dwordx4 v[68:71], v4, s[16:17] offset:64
	global_load_dwordx4 v[72:75], v4, s[16:17] offset:128
	global_load_dwordx4 v[76:79], v4, s[16:17] offset:192
	global_load_dwordx4 v[80:83], v4, s[18:19] offset:0
	global_load_dwordx4 v[84:87], v4, s[18:19] offset:64
	global_load_dwordx4 v[88:91], v4, s[18:19] offset:128
	global_load_dwordx4 v[92:95], v4, s[18:19] offset:192
	global_load_dwordx4 v[96:99], v4, s[20:21] offset:0
	global_load_dwordx4 v[100:103], v4, s[20:21] offset:64
	global_load_dwordx4 v[104:107], v4, s[20:21] offset:128
	global_load_dwordx4 v[108:111], v4, s[20:21] offset:192
	s_add_u32 s22, s4, 0x30501000
	s_addc_u32 s23, s5, 0
	s_lshl_b32 s3, s7, 12
	s_add_u32 s22, s22, s3
	s_addc_u32 s23, s23, 0
	s_lshl_b32 s3, s8, 11
	s_add_u32 s22, s22, s3
	s_addc_u32 s23, s23, 0
	s_lshl_b32 s3, s11, 10
	s_add_u32 s22, s22, s3
	s_addc_u32 s23, s23, 0
	v_lshl_add_u32 v12, s10, 6, v10
	global_load_dword v20, v12, s[22:23] offset:0
	global_load_dwordx4 v[128:131], v3, s[22:23] offset:0
	global_load_dwordx4 v[132:135], v3, s[22:23] offset:64
	global_load_dwordx4 v[136:139], v3, s[22:23] offset:128
	global_load_dwordx4 v[140:143], v3, s[22:23] offset:192
	global_load_dword v21, v12, s[22:23] offset:256
; __device__ __forceinline__ u32x2 pk4(f32x4 v) { u32x2 r; r.x = pk2(v[0], v[1]); r.y = pk2(v[2], v[3]); return r; }
;     template <class Tp> __device__ __forceinline__ Tp* W(size_t off) const { return (Tp*)(ws + off); }
; __device__ void ssd_mm(const Ctx& c, int ck, int g, int lb) {
;     ...
;     const int l = lb * 16 + r;
;     for (int hh = 0; hh < 8; ++hh) { const int h = g * 8 + hh; const float* ac = sAcs + (size_t)(ck * 16 + h) * 64; const float al = ac[l];
; #pragma unroll
;         for (int sb = 0; sb < 4; ++sb) { const f32x4 as = *(const f32x4*)(ac + sb * 16 + 4 * q); f32x4 o;
; #pragma unroll
;             for (int j = 0; j < 4; ++j) { const int s = sb * 16 + 4 * q + j; o[j] = (s <= l) ? cb[sb][j] * __expf(al - as[j]) : 0.f; }
;             *(u32x2*)(sMm + ((size_t)(ck * 16 + h) * 64 + l) * 64 + sb * 16 + 4 * q) = pk4(o); } }
; __device__ void ssd_s1(const Ctx& c, int ck, int h) {
;     const bf16_t* sXw = c.W<bf16_t>(WS_SXW); const bf16_t* sBT = c.W<bf16_t>(WS_SBT); bf16_t* sSt = c.W<bf16_t>(WS_SST);
;     const int r = c.r, q = c.q, g = h >> 3; const size_t chh = (size_t)(ck * 16 + h);
;     bf16x8 xw[4][2];
; #pragma unroll
;     for (int pb = 0; pb < 4; ++pb)
; #pragma unroll
;         for (int kk = 0; kk < 2; ++kk) xw[pb][kk] = ldfrag(sXw + (chh * 64 + pb * 16 + r) * 64 + kk * 32 + q * 8);
; #pragma unroll
;     for (int nb = 0; nb < 8; ++nb) { bf16x8 bt[2];
; #pragma unroll
;         for (int kk = 0; kk < 2; ++kk) bt[kk] = ldfrag(sBT + ((size_t)(ck * 2 + g) * 128 + nb * 16 + r) * 64 + kk * 32 + q * 8);
	global_load_dwordx4 v[144:147], v3, s[22:23] offset:256
	global_load_dwordx4 v[148:151], v3, s[22:23] offset:320
	global_load_dwordx4 v[152:155], v3, s[22:23] offset:384
	global_load_dwordx4 v[156:159], v3, s[22:23] offset:448
	global_load_dword v22, v12, s[22:23] offset:512
	global_load_dwordx4 v[160:163], v3, s[22:23] offset:512
	global_load_dwordx4 v[164:167], v3, s[22:23] offset:576
	global_load_dwordx4 v[168:171], v3, s[22:23] offset:640
	global_load_dwordx4 v[172:175], v3, s[22:23] offset:704
	global_load_dword v23, v12, s[22:23] offset:768
	global_load_dwordx4 v[192:195], v3, s[22:23] offset:768
	global_load_dwordx4 v[196:199], v3, s[22:23] offset:832
	global_load_dwordx4 v[200:203], v3, s[22:23] offset:896
	global_load_dwordx4 v[204:207], v3, s[22:23] offset:960
	v_lshl_add_u32 v13, s10, 4, v1
	v_add_u32_e32 v14, 0, v11
	v_cmp_le_u32_e64 s[32:33], v14, v13
	v_add_u32_e32 v14, 1, v11
	v_cmp_le_u32_e64 s[34:35], v14, v13
	v_add_u32_e32 v14, 2, v11
	v_cmp_le_u32_e64 s[36:37], v14, v13
	v_add_u32_e32 v14, 3, v11
	v_cmp_le_u32_e64 s[38:39], v14, v13
	v_add_u32_e32 v14, 16, v11
	v_cmp_le_u32_e64 s[40:41], v14, v13
	v_add_u32_e32 v14, 17, v11
	v_cmp_le_u32_e64 s[42:43], v14, v13
	v_add_u32_e32 v14, 18, v11
	v_cmp_le_u32_e64 s[44:45], v14, v13
	v_add_u32_e32 v14, 19, v11
	v_cmp_le_u32_e64 s[46:47], v14, v13
	v_add_u32_e32 v14, 32, v11
	v_cmp_le_u32_e64 s[48:49], v14, v13
	v_add_u32_e32 v14, 33, v11
	v_cmp_le_u32_e64 s[50:51], v14, v13
	v_add_u32_e32 v14, 34, v11
	v_cmp_le_u32_e64 s[52:53], v14, v13
	v_add_u32_e32 v14, 35, v11
	v_cmp_le_u32_e64 s[54:55], v14, v13
	v_add_u32_e32 v14, 48, v11
	v_cmp_le_u32_e64 s[56:57], v14, v13
	v_add_u32_e32 v14, 49, v11
	v_cmp_le_u32_e64 s[58:59], v14, v13
	v_add_u32_e32 v14, 50, v11
	v_cmp_le_u32_e64 s[60:61], v14, v13
	v_add_u32_e32 v14, 51, v11
	v_cmp_le_u32_e64 s[62:63], v14, v13
	s_waitcnt vmcnt(20)
	v_mfma_f32_16x16x32_bf16 v[212:215], v[32:35], v[96:99], 0
	v_mfma_f32_16x16x32_bf16 v[212:215], v[36:39], v[100:103], v[212:215]
	v_mfma_f32_16x16x32_bf16 v[212:215], v[40:43], v[104:107], v[212:215]
	v_mfma_f32_16x16x32_bf16 v[212:215], v[44:47], v[108:111], v[212:215]
	v_mfma_f32_16x16x32_bf16 v[216:219], v[48:51], v[96:99], 0
	v_mfma_f32_16x16x32_bf16 v[216:219], v[52:55], v[100:103], v[216:219]
	v_mfma_f32_16x16x32_bf16 v[216:219], v[56:59], v[104:107], v[216:219]
	v_mfma_f32_16x16x32_bf16 v[216:219], v[60:63], v[108:111], v[216:219]
	v_mfma_f32_16x16x32_bf16 v[220:223], v[64:67], v[96:99], 0
	v_mfma_f32_16x16x32_bf16 v[220:223], v[68:71], v[100:103], v[220:223]
	v_mfma_f32_16x16x32_bf16 v[220:223], v[72:75], v[104:107], v[220:223]
	v_mfma_f32_16x16x32_bf16 v[220:223], v[76:79], v[108:111], v[220:223]
	v_mfma_f32_16x16x32_bf16 v[224:227], v[80:83], v[96:99], 0
	v_mfma_f32_16x16x32_bf16 v[224:227], v[84:87], v[100:103], v[224:227]
	v_mfma_f32_16x16x32_bf16 v[224:227], v[88:91], v[104:107], v[224:227]
	v_mfma_f32_16x16x32_bf16 v[224:227], v[92:95], v[108:111], v[224:227]
	s_nop 7
	s_nop 7
	s_lshl_b32 s2, s7, 4
	s_lshl_b32 s3, s8, 3
	s_add_i32 s2, s2, s3
	s_add_i32 s2, s2, s9
	s_mov_b32 s31, s2
	s_add_u32 s24, s4, 0x2b901000
	s_addc_u32 s25, s5, 0
	s_lshl_b32 s3, s31, 13
	s_add_u32 s24, s24, s3
	s_addc_u32 s25, s25, 0
	s_add_u32 s26, s24, 0x1000
	s_addc_u32 s27, s25, 0
	global_load_dwordx4 v[32:35], v5, s[24:25] offset:0
	global_load_dwordx4 v[36:39], v5, s[24:25] offset:64
	global_load_dwordx4 v[40:43], v5, s[24:25] offset:2048
	global_load_dwordx4 v[44:47], v5, s[24:25] offset:2112
	global_load_dwordx4 v[48:51], v5, s[26:27] offset:0
	global_load_dwordx4 v[52:55], v5, s[26:27] offset:64
	global_load_dwordx4 v[56:59], v5, s[26:27] offset:2048
	global_load_dwordx4 v[60:63], v5, s[26:27] offset:2112
	s_add_u32 s28, s4, 0x2d101000
	s_addc_u32 s29, s5, 0
	s_lshl_b32 s3, s7, 15
	s_add_u32 s28, s28, s3
	s_addc_u32 s29, s29, 0
	s_lshl_b32 s3, s8, 14
	s_add_u32 s28, s28, s3
	s_addc_u32 s29, s29, 0
	s_add_u32 s64, s28, 0x1000
	s_addc_u32 s65, s29, 0
	s_add_u32 s66, s28, 0x2000
	s_addc_u32 s67, s29, 0
	s_add_u32 s68, s28, 0x3000
	s_addc_u32 s69, s29, 0
	global_load_dwordx4 v[64:67], v5, s[28:29] offset:0
	global_load_dwordx4 v[68:71], v5, s[28:29] offset:64
	global_load_dwordx4 v[72:75], v5, s[28:29] offset:2048
	global_load_dwordx4 v[76:79], v5, s[28:29] offset:2112
	global_load_dwordx4 v[80:83], v5, s[64:65] offset:0
	global_load_dwordx4 v[84:87], v5, s[64:65] offset:64
	global_load_dwordx4 v[88:91], v5, s[64:65] offset:2048
	global_load_dwordx4 v[92:95], v5, s[64:65] offset:2112
	global_load_dwordx4 v[96:99], v5, s[66:67] offset:0
	global_load_dwordx4 v[100:103], v5, s[66:67] offset:64
	global_load_dwordx4 v[104:107], v5, s[66:67] offset:2048
	global_load_dwordx4 v[108:111], v5, s[66:67] offset:2112
	global_load_dwordx4 v[112:115], v5, s[68:69] offset:0
	global_load_dwordx4 v[116:119], v5, s[68:69] offset:64
	global_load_dwordx4 v[120:123], v5, s[68:69] offset:2048
	global_load_dwordx4 v[124:127], v5, s[68:69] offset:2112
	s_waitcnt vmcnt(24)
; __device__ __forceinline__ u32x2 pk4(f32x4 v) { u32x2 r; r.x = pk2(v[0], v[1]); r.y = pk2(v[2], v[3]); return r; }
; __device__ void ssd_mm(const Ctx& c, int ck, int g, int lb) {
;     ...
;     for (int hh = 0; hh < 8; ++hh) { const int h = g * 8 + hh; const float* ac = sAcs + (size_t)(ck * 16 + h) * 64; const float al = ac[l];
; #pragma unroll
;         for (int sb = 0; sb < 4; ++sb) { const f32x4 as = *(const f32x4*)(ac + sb * 16 + 4 * q); f32x4 o;
; #pragma unroll
;             for (int j = 0; j < 4; ++j) { const int s = sb * 16 + 4 * q + j; o[j] = (s <= l) ? cb[sb][j] * __expf(al - as[j]) : 0.f; }
;             *(u32x2*)(sMm + ((size_t)(ck * 16 + h) * 64 + l) * 64 + sb * 16 + 4 * q) = pk4(o); } }
	s_add_u32 s70, s4, 0x2d501000
	s_addc_u32 s71, s5, 0
	s_lshl_b32 s3, s7, 17
	s_add_u32 s70, s70, s3
	s_addc_u32 s71, s71, 0
	s_lshl_b32 s3, s8, 16
	s_add_u32 s70, s70, s3
	s_addc_u32 s71, s71, 0
	s_lshl_b32 s3, s11, 15
	s_add_u32 s70, s70, s3
	s_addc_u32 s71, s71, 0
	s_add_u32 s72, s70, 0x2000
	s_addc_u32 s73, s71, 0
	s_add_u32 s74, s70, 0x4000
	s_addc_u32 s75, s71, 0
	s_add_u32 s76, s70, 0x6000
	s_addc_u32 s77, s71, 0
	v_lshl_add_u32 v15, v13, 7, v7
	v_sub_f32_e32 v128, v20, v128
	v_sub_f32_e32 v129, v20, v129
	v_sub_f32_e32 v130, v20, v130
	v_sub_f32_e32 v131, v20, v131
	v_mul_f32_e32 v128, 0x3fb8aa3b, v128
	v_mul_f32_e32 v129, 0x3fb8aa3b, v129
	v_mul_f32_e32 v130, 0x3fb8aa3b, v130
	v_mul_f32_e32 v131, 0x3fb8aa3b, v131
	v_exp_f32_e32 v128, v128
	v_exp_f32_e32 v129, v129
	v_exp_f32_e32 v130, v130
	v_exp_f32_e32 v131, v131
	s_nop 0
	v_mul_f32_e32 v128, v212, v128
	v_mul_f32_e32 v129, v213, v129
	v_mul_f32_e32 v130, v214, v130
	v_mul_f32_e32 v131, v215, v131
	v_cndmask_b32_e64 v128, 0, v128, s[32:33]
	v_cndmask_b32_e64 v129, 0, v129, s[34:35]
	v_cndmask_b32_e64 v130, 0, v130, s[36:37]
	v_cndmask_b32_e64 v131, 0, v131, s[38:39]
	v_cvt_pk_bf16_f32 v128, v128, v129
	v_cvt_pk_bf16_f32 v129, v130, v131
	global_store_dwordx2 v15, v[128:129], s[70:71] offset:0
	v_sub_f32_e32 v132, v20, v132
	v_sub_f32_e32 v133, v20, v133
	v_sub_f32_e32 v134, v20, v134
	v_sub_f32_e32 v135, v20, v135
	v_mul_f32_e32 v132, 0x3fb8aa3b, v132
	v_mul_f32_e32 v133, 0x3fb8aa3b, v133
	v_mul_f32_e32 v134, 0x3fb8aa3b, v134
	v_mul_f32_e32 v135, 0x3fb8aa3b, v135
	v_exp_f32_e32 v132, v132
	v_exp_f32_e32 v133, v133
	v_exp_f32_e32 v134, v134
	v_exp_f32_e32 v135, v135
	s_nop 0
	v_mul_f32_e32 v132, v216, v132
	v_mul_f32_e32 v133, v217, v133
	v_mul_f32_e32 v134, v218, v134
	v_mul_f32_e32 v135, v219, v135
	v_cndmask_b32_e64 v132, 0, v132, s[40:41]
	v_cndmask_b32_e64 v133, 0, v133, s[42:43]
	v_cndmask_b32_e64 v134, 0, v134, s[44:45]
	v_cndmask_b32_e64 v135, 0, v135, s[46:47]
	v_cvt_pk_bf16_f32 v132, v132, v133
	v_cvt_pk_bf16_f32 v133, v134, v135
	global_store_dwordx2 v15, v[132:133], s[70:71] offset:32
	v_sub_f32_e32 v136, v20, v136
	v_sub_f32_e32 v137, v20, v137
	v_sub_f32_e32 v138, v20, v138
	v_sub_f32_e32 v139, v20, v139
	v_mul_f32_e32 v136, 0x3fb8aa3b, v136
	v_mul_f32_e32 v137, 0x3fb8aa3b, v137
	v_mul_f32_e32 v138, 0x3fb8aa3b, v138
	v_mul_f32_e32 v139, 0x3fb8aa3b, v139
	v_exp_f32_e32 v136, v136
	v_exp_f32_e32 v137, v137
	v_exp_f32_e32 v138, v138
	v_exp_f32_e32 v139, v139
	s_nop 0
	v_mul_f32_e32 v136, v220, v136
	v_mul_f32_e32 v137, v221, v137
	v_mul_f32_e32 v138, v222, v138
	v_mul_f32_e32 v139, v223, v139
	v_cndmask_b32_e64 v136, 0, v136, s[48:49]
	v_cndmask_b32_e64 v137, 0, v137, s[50:51]
	v_cndmask_b32_e64 v138, 0, v138, s[52:53]
	v_cndmask_b32_e64 v139, 0, v139, s[54:55]
	v_cvt_pk_bf16_f32 v136, v136, v137
	v_cvt_pk_bf16_f32 v137, v138, v139
	global_store_dwordx2 v15, v[136:137], s[70:71] offset:64
	v_sub_f32_e32 v140, v20, v140
	v_sub_f32_e32 v141, v20, v141
	v_sub_f32_e32 v142, v20, v142
	v_sub_f32_e32 v143, v20, v143
	v_mul_f32_e32 v140, 0x3fb8aa3b, v140
	v_mul_f32_e32 v141, 0x3fb8aa3b, v141
	v_mul_f32_e32 v142, 0x3fb8aa3b, v142
	v_mul_f32_e32 v143, 0x3fb8aa3b, v143
	v_exp_f32_e32 v140, v140
	v_exp_f32_e32 v141, v141
	v_exp_f32_e32 v142, v142
	v_exp_f32_e32 v143, v143
	s_nop 0
	v_mul_f32_e32 v140, v224, v140
	v_mul_f32_e32 v141, v225, v141
	v_mul_f32_e32 v142, v226, v142
	v_mul_f32_e32 v143, v227, v143
	v_cndmask_b32_e64 v140, 0, v140, s[56:57]
	v_cndmask_b32_e64 v141, 0, v141, s[58:59]
	v_cndmask_b32_e64 v142, 0, v142, s[60:61]
	v_cndmask_b32_e64 v143, 0, v143, s[62:63]
	v_cvt_pk_bf16_f32 v140, v140, v141
	v_cvt_pk_bf16_f32 v141, v142, v143
	global_store_dwordx2 v15, v[140:141], s[70:71] offset:96
	v_sub_f32_e32 v144, v21, v144
	v_sub_f32_e32 v145, v21, v145
	v_sub_f32_e32 v146, v21, v146
	v_sub_f32_e32 v147, v21, v147
	v_mul_f32_e32 v144, 0x3fb8aa3b, v144
	v_mul_f32_e32 v145, 0x3fb8aa3b, v145
	v_mul_f32_e32 v146, 0x3fb8aa3b, v146
	v_mul_f32_e32 v147, 0x3fb8aa3b, v147
	v_exp_f32_e32 v144, v144
	v_exp_f32_e32 v145, v145
	v_exp_f32_e32 v146, v146
	v_exp_f32_e32 v147, v147
	s_nop 0
	v_mul_f32_e32 v144, v212, v144
	v_mul_f32_e32 v145, v213, v145
	v_mul_f32_e32 v146, v214, v146
	v_mul_f32_e32 v147, v215, v147
	v_cndmask_b32_e64 v144, 0, v144, s[32:33]
	v_cndmask_b32_e64 v145, 0, v145, s[34:35]
	v_cndmask_b32_e64 v146, 0, v146, s[36:37]
	v_cndmask_b32_e64 v147, 0, v147, s[38:39]
	v_cvt_pk_bf16_f32 v144, v144, v145
	v_cvt_pk_bf16_f32 v145, v146, v147
	global_store_dwordx2 v15, v[144:145], s[72:73] offset:0
	v_sub_f32_e32 v148, v21, v148
	v_sub_f32_e32 v149, v21, v149
	v_sub_f32_e32 v150, v21, v150
	v_sub_f32_e32 v151, v21, v151
	v_mul_f32_e32 v148, 0x3fb8aa3b, v148
	v_mul_f32_e32 v149, 0x3fb8aa3b, v149
	v_mul_f32_e32 v150, 0x3fb8aa3b, v150
	v_mul_f32_e32 v151, 0x3fb8aa3b, v151
	v_exp_f32_e32 v148, v148
	v_exp_f32_e32 v149, v149
	v_exp_f32_e32 v150, v150
	v_exp_f32_e32 v151, v151
	s_nop 0
	v_mul_f32_e32 v148, v216, v148
	v_mul_f32_e32 v149, v217, v149
	v_mul_f32_e32 v150, v218, v150
	v_mul_f32_e32 v151, v219, v151
	v_cndmask_b32_e64 v148, 0, v148, s[40:41]
	v_cndmask_b32_e64 v149, 0, v149, s[42:43]
	v_cndmask_b32_e64 v150, 0, v150, s[44:45]
	v_cndmask_b32_e64 v151, 0, v151, s[46:47]
	v_cvt_pk_bf16_f32 v148, v148, v149
	v_cvt_pk_bf16_f32 v149, v150, v151
	global_store_dwordx2 v15, v[148:149], s[72:73] offset:32
	v_sub_f32_e32 v152, v21, v152
	v_sub_f32_e32 v153, v21, v153
	v_sub_f32_e32 v154, v21, v154
	v_sub_f32_e32 v155, v21, v155
	v_mul_f32_e32 v152, 0x3fb8aa3b, v152
	v_mul_f32_e32 v153, 0x3fb8aa3b, v153
	v_mul_f32_e32 v154, 0x3fb8aa3b, v154
	v_mul_f32_e32 v155, 0x3fb8aa3b, v155
; __device__ __forceinline__ u32x2 pk4(f32x4 v) { u32x2 r; r.x = pk2(v[0], v[1]); r.y = pk2(v[2], v[3]); return r; }
; __device__ void ssd_mm(const Ctx& c, int ck, int g, int lb) {
;     ...
;     for (int hh = 0; hh < 8; ++hh) { const int h = g * 8 + hh; const float* ac = sAcs + (size_t)(ck * 16 + h) * 64; const float al = ac[l];
; #pragma unroll
;         for (int sb = 0; sb < 4; ++sb) { const f32x4 as = *(const f32x4*)(ac + sb * 16 + 4 * q); f32x4 o;
; #pragma unroll
;             for (int j = 0; j < 4; ++j) { const int s = sb * 16 + 4 * q + j; o[j] = (s <= l) ? cb[sb][j] * __expf(al - as[j]) : 0.f; }
;             *(u32x2*)(sMm + ((size_t)(ck * 16 + h) * 64 + l) * 64 + sb * 16 + 4 * q) = pk4(o); } }
	v_exp_f32_e32 v152, v152
	v_exp_f32_e32 v153, v153
	v_exp_f32_e32 v154, v154
	v_exp_f32_e32 v155, v155
	s_nop 0
	v_mul_f32_e32 v152, v220, v152
	v_mul_f32_e32 v153, v221, v153
	v_mul_f32_e32 v154, v222, v154
	v_mul_f32_e32 v155, v223, v155
	v_cndmask_b32_e64 v152, 0, v152, s[48:49]
	v_cndmask_b32_e64 v153, 0, v153, s[50:51]
	v_cndmask_b32_e64 v154, 0, v154, s[52:53]
	v_cndmask_b32_e64 v155, 0, v155, s[54:55]
	v_cvt_pk_bf16_f32 v152, v152, v153
	v_cvt_pk_bf16_f32 v153, v154, v155
	global_store_dwordx2 v15, v[152:153], s[72:73] offset:64
	v_sub_f32_e32 v156, v21, v156
	v_sub_f32_e32 v157, v21, v157
	v_sub_f32_e32 v158, v21, v158
	v_sub_f32_e32 v159, v21, v159
	v_mul_f32_e32 v156, 0x3fb8aa3b, v156
	v_mul_f32_e32 v157, 0x3fb8aa3b, v157
	v_mul_f32_e32 v158, 0x3fb8aa3b, v158
	v_mul_f32_e32 v159, 0x3fb8aa3b, v159
	v_exp_f32_e32 v156, v156
	v_exp_f32_e32 v157, v157
	v_exp_f32_e32 v158, v158
	v_exp_f32_e32 v159, v159
	s_nop 0
	v_mul_f32_e32 v156, v224, v156
	v_mul_f32_e32 v157, v225, v157
	v_mul_f32_e32 v158, v226, v158
	v_mul_f32_e32 v159, v227, v159
	v_cndmask_b32_e64 v156, 0, v156, s[56:57]
	v_cndmask_b32_e64 v157, 0, v157, s[58:59]
	v_cndmask_b32_e64 v158, 0, v158, s[60:61]
	v_cndmask_b32_e64 v159, 0, v159, s[62:63]
	v_cvt_pk_bf16_f32 v156, v156, v157
	v_cvt_pk_bf16_f32 v157, v158, v159
	global_store_dwordx2 v15, v[156:157], s[72:73] offset:96
	v_sub_f32_e32 v160, v22, v160
	v_sub_f32_e32 v161, v22, v161
	v_sub_f32_e32 v162, v22, v162
	v_sub_f32_e32 v163, v22, v163
	v_mul_f32_e32 v160, 0x3fb8aa3b, v160
	v_mul_f32_e32 v161, 0x3fb8aa3b, v161
	v_mul_f32_e32 v162, 0x3fb8aa3b, v162
	v_mul_f32_e32 v163, 0x3fb8aa3b, v163
	v_exp_f32_e32 v160, v160
	v_exp_f32_e32 v161, v161
	v_exp_f32_e32 v162, v162
	v_exp_f32_e32 v163, v163
	s_nop 0
	v_mul_f32_e32 v160, v212, v160
	v_mul_f32_e32 v161, v213, v161
	v_mul_f32_e32 v162, v214, v162
	v_mul_f32_e32 v163, v215, v163
	v_cndmask_b32_e64 v160, 0, v160, s[32:33]
	v_cndmask_b32_e64 v161, 0, v161, s[34:35]
	v_cndmask_b32_e64 v162, 0, v162, s[36:37]
	v_cndmask_b32_e64 v163, 0, v163, s[38:39]
	v_cvt_pk_bf16_f32 v160, v160, v161
	v_cvt_pk_bf16_f32 v161, v162, v163
	global_store_dwordx2 v15, v[160:161], s[74:75] offset:0
	v_sub_f32_e32 v164, v22, v164
	v_sub_f32_e32 v165, v22, v165
	v_sub_f32_e32 v166, v22, v166
	v_sub_f32_e32 v167, v22, v167
	v_mul_f32_e32 v164, 0x3fb8aa3b, v164
	v_mul_f32_e32 v165, 0x3fb8aa3b, v165
	v_mul_f32_e32 v166, 0x3fb8aa3b, v166
	v_mul_f32_e32 v167, 0x3fb8aa3b, v167
	v_exp_f32_e32 v164, v164
	v_exp_f32_e32 v165, v165
	v_exp_f32_e32 v166, v166
	v_exp_f32_e32 v167, v167
	s_nop 0
	v_mul_f32_e32 v164, v216, v164
	v_mul_f32_e32 v165, v217, v165
	v_mul_f32_e32 v166, v218, v166
	v_mul_f32_e32 v167, v219, v167
	v_cndmask_b32_e64 v164, 0, v164, s[40:41]
	v_cndmask_b32_e64 v165, 0, v165, s[42:43]
	v_cndmask_b32_e64 v166, 0, v166, s[44:45]
	v_cndmask_b32_e64 v167, 0, v167, s[46:47]
	v_cvt_pk_bf16_f32 v164, v164, v165
	v_cvt_pk_bf16_f32 v165, v166, v167
	global_store_dwordx2 v15, v[164:165], s[74:75] offset:32
	v_sub_f32_e32 v168, v22, v168
	v_sub_f32_e32 v169, v22, v169
	v_sub_f32_e32 v170, v22, v170
	v_sub_f32_e32 v171, v22, v171
	v_mul_f32_e32 v168, 0x3fb8aa3b, v168
	v_mul_f32_e32 v169, 0x3fb8aa3b, v169
	v_mul_f32_e32 v170, 0x3fb8aa3b, v170
	v_mul_f32_e32 v171, 0x3fb8aa3b, v171
	v_exp_f32_e32 v168, v168
	v_exp_f32_e32 v169, v169
	v_exp_f32_e32 v170, v170
	v_exp_f32_e32 v171, v171
	s_nop 0
	v_mul_f32_e32 v168, v220, v168
	v_mul_f32_e32 v169, v221, v169
	v_mul_f32_e32 v170, v222, v170
	v_mul_f32_e32 v171, v223, v171
	v_cndmask_b32_e64 v168, 0, v168, s[48:49]
	v_cndmask_b32_e64 v169, 0, v169, s[50:51]
	v_cndmask_b32_e64 v170, 0, v170, s[52:53]
	v_cndmask_b32_e64 v171, 0, v171, s[54:55]
	v_cvt_pk_bf16_f32 v168, v168, v169
	v_cvt_pk_bf16_f32 v169, v170, v171
	global_store_dwordx2 v15, v[168:169], s[74:75] offset:64
	v_sub_f32_e32 v172, v22, v172
	v_sub_f32_e32 v173, v22, v173
	v_sub_f32_e32 v174, v22, v174
	v_sub_f32_e32 v175, v22, v175
	v_mul_f32_e32 v172, 0x3fb8aa3b, v172
	v_mul_f32_e32 v173, 0x3fb8aa3b, v173
	v_mul_f32_e32 v174, 0x3fb8aa3b, v174
	v_mul_f32_e32 v175, 0x3fb8aa3b, v175
	v_exp_f32_e32 v172, v172
	v_exp_f32_e32 v173, v173
	v_exp_f32_e32 v174, v174
	v_exp_f32_e32 v175, v175
	s_nop 0
	v_mul_f32_e32 v172, v224, v172
	v_mul_f32_e32 v173, v225, v173
	v_mul_f32_e32 v174, v226, v174
	v_mul_f32_e32 v175, v227, v175
	v_cndmask_b32_e64 v172, 0, v172, s[56:57]
	v_cndmask_b32_e64 v173, 0, v173, s[58:59]
	v_cndmask_b32_e64 v174, 0, v174, s[60:61]
	v_cndmask_b32_e64 v175, 0, v175, s[62:63]
	v_cvt_pk_bf16_f32 v172, v172, v173
	v_cvt_pk_bf16_f32 v173, v174, v175
	global_store_dwordx2 v15, v[172:173], s[74:75] offset:96
	v_sub_f32_e32 v192, v23, v192
	v_sub_f32_e32 v193, v23, v193
	v_sub_f32_e32 v194, v23, v194
	v_sub_f32_e32 v195, v23, v195
	v_mul_f32_e32 v192, 0x3fb8aa3b, v192
	v_mul_f32_e32 v193, 0x3fb8aa3b, v193
	v_mul_f32_e32 v194, 0x3fb8aa3b, v194
	v_mul_f32_e32 v195, 0x3fb8aa3b, v195
	v_exp_f32_e32 v192, v192
	v_exp_f32_e32 v193, v193
	v_exp_f32_e32 v194, v194
	v_exp_f32_e32 v195, v195
	s_nop 0
	v_mul_f32_e32 v192, v212, v192
	v_mul_f32_e32 v193, v213, v193
	v_mul_f32_e32 v194, v214, v194
	v_mul_f32_e32 v195, v215, v195
	v_cndmask_b32_e64 v192, 0, v192, s[32:33]
	v_cndmask_b32_e64 v193, 0, v193, s[34:35]
	v_cndmask_b32_e64 v194, 0, v194, s[36:37]
	v_cndmask_b32_e64 v195, 0, v195, s[38:39]
	v_cvt_pk_bf16_f32 v192, v192, v193
	v_cvt_pk_bf16_f32 v193, v194, v195
	global_store_dwordx2 v15, v[192:193], s[76:77] offset:0
	v_sub_f32_e32 v196, v23, v196
	v_sub_f32_e32 v197, v23, v197
	v_sub_f32_e32 v198, v23, v198
	v_sub_f32_e32 v199, v23, v199
	v_mul_f32_e32 v196, 0x3fb8aa3b, v196
	v_mul_f32_e32 v197, 0x3fb8aa3b, v197
; __device__ __forceinline__ u32x2 pk4(f32x4 v) { u32x2 r; r.x = pk2(v[0], v[1]); r.y = pk2(v[2], v[3]); return r; }
; __device__ __forceinline__ f32x4 mfma16(bf16x8 a, bf16x8 b, f32x4 c) { return __builtin_amdgcn_mfma_f32_16x16x32_bf16(a, b, c, 0, 0, 0); }
;     template <class Tp> __device__ __forceinline__ Tp* W(size_t off) const { return (Tp*)(ws + off); }
; __device__ void ssd_s1(const Ctx& c, int ck, int h) {
;     ...
;     for (int nb = 0; nb < 8; ++nb) { bf16x8 bt[2];
; #pragma unroll
;         for (int kk = 0; kk < 2; ++kk) bt[kk] = ldfrag(sBT + ((size_t)(ck * 2 + g) * 128 + nb * 16 + r) * 64 + kk * 32 + q * 8);
; #pragma unroll
;         for (int pb = 0; pb < 4; ++pb) { f32x4 a = (f32x4){0.f, 0.f, 0.f, 0.f};
; #pragma unroll
;             for (int kk = 0; kk < 2; ++kk) a = mfma16(bt[kk], xw[pb][kk], a);
;             *(u32x2*)(sSt + (chh * 64 + pb * 16 + r) * 128 + nb * 16 + 4 * q) = pk4(a); } }
; __device__ void gla_attn(const Ctx& c, int ck, int h, int ib) {
;     const bf16_t* gQg = c.W<bf16_t>(WS_GQG); const bf16_t* gKn = c.W<bf16_t>(WS_GKN); bf16_t* gAtt = c.W<bf16_t>(WS_GATT);
;     const int r = c.r, q = c.q; const size_t chh = (size_t)(ck * 4 + h); const int i = ib * 16 + r;
; #pragma unroll
;     for (int jb = 0; jb < 4; ++jb) { f32x4 a = (f32x4){0.f, 0.f, 0.f, 0.f};
;         if (jb <= ib) {
; #pragma unroll
;             for (int k0 = 0; k0 < 128; k0 += 32)
;                 a = mfma16(ldfrag(gKn + (chh * 64 + jb * 16 + r) * 128 + k0 + q * 8), ldfrag(gQg + (chh * 64 + i) * 128 + k0 + q * 8), a);
	v_mul_f32_e32 v198, 0x3fb8aa3b, v198
	v_mul_f32_e32 v199, 0x3fb8aa3b, v199
	v_exp_f32_e32 v196, v196
	v_exp_f32_e32 v197, v197
	v_exp_f32_e32 v198, v198
	v_exp_f32_e32 v199, v199
	s_nop 0
	v_mul_f32_e32 v196, v216, v196
	v_mul_f32_e32 v197, v217, v197
	v_mul_f32_e32 v198, v218, v198
	v_mul_f32_e32 v199, v219, v199
	v_cndmask_b32_e64 v196, 0, v196, s[40:41]
	v_cndmask_b32_e64 v197, 0, v197, s[42:43]
	v_cndmask_b32_e64 v198, 0, v198, s[44:45]
	v_cndmask_b32_e64 v199, 0, v199, s[46:47]
	v_cvt_pk_bf16_f32 v196, v196, v197
	v_cvt_pk_bf16_f32 v197, v198, v199
	global_store_dwordx2 v15, v[196:197], s[76:77] offset:32
	v_sub_f32_e32 v200, v23, v200
	v_sub_f32_e32 v201, v23, v201
	v_sub_f32_e32 v202, v23, v202
	v_sub_f32_e32 v203, v23, v203
	v_mul_f32_e32 v200, 0x3fb8aa3b, v200
	v_mul_f32_e32 v201, 0x3fb8aa3b, v201
	v_mul_f32_e32 v202, 0x3fb8aa3b, v202
	v_mul_f32_e32 v203, 0x3fb8aa3b, v203
	v_exp_f32_e32 v200, v200
	v_exp_f32_e32 v201, v201
	v_exp_f32_e32 v202, v202
	v_exp_f32_e32 v203, v203
	s_nop 0
	v_mul_f32_e32 v200, v220, v200
	v_mul_f32_e32 v201, v221, v201
	v_mul_f32_e32 v202, v222, v202
	v_mul_f32_e32 v203, v223, v203
	v_cndmask_b32_e64 v200, 0, v200, s[48:49]
	v_cndmask_b32_e64 v201, 0, v201, s[50:51]
	v_cndmask_b32_e64 v202, 0, v202, s[52:53]
	v_cndmask_b32_e64 v203, 0, v203, s[54:55]
	v_cvt_pk_bf16_f32 v200, v200, v201
	v_cvt_pk_bf16_f32 v201, v202, v203
	global_store_dwordx2 v15, v[200:201], s[76:77] offset:64
	v_sub_f32_e32 v204, v23, v204
	v_sub_f32_e32 v205, v23, v205
	v_sub_f32_e32 v206, v23, v206
	v_sub_f32_e32 v207, v23, v207
	v_mul_f32_e32 v204, 0x3fb8aa3b, v204
	v_mul_f32_e32 v205, 0x3fb8aa3b, v205
	v_mul_f32_e32 v206, 0x3fb8aa3b, v206
	v_mul_f32_e32 v207, 0x3fb8aa3b, v207
	v_exp_f32_e32 v204, v204
	v_exp_f32_e32 v205, v205
	v_exp_f32_e32 v206, v206
	v_exp_f32_e32 v207, v207
	s_nop 0
	v_mul_f32_e32 v204, v224, v204
	v_mul_f32_e32 v205, v225, v205
	v_mul_f32_e32 v206, v226, v206
	v_mul_f32_e32 v207, v227, v207
	v_cndmask_b32_e64 v204, 0, v204, s[56:57]
	v_cndmask_b32_e64 v205, 0, v205, s[58:59]
	v_cndmask_b32_e64 v206, 0, v206, s[60:61]
	v_cndmask_b32_e64 v207, 0, v207, s[62:63]
	v_cvt_pk_bf16_f32 v204, v204, v205
	v_cvt_pk_bf16_f32 v205, v206, v207
	global_store_dwordx2 v15, v[204:205], s[76:77] offset:96
	s_nop 1
	s_lshl_b32 s2, s7, 2
	s_lshl_b32 s3, s8, 1
	s_add_i32 s2, s2, s3
	s_add_i32 s30, s2, s11
	s_add_u32 s78, s4, 0x30581000
	s_addc_u32 s79, s5, 0
	s_lshl_b32 s3, s30, 14
	s_add_u32 s78, s78, s3
	s_addc_u32 s79, s79, 0
	s_lshl_b32 s3, s10, 12
	s_add_u32 s78, s78, s3
	s_addc_u32 s79, s79, 0
	global_load_dwordx4 v[128:131], v6, s[78:79] offset:0
	global_load_dwordx4 v[132:135], v6, s[78:79] offset:64
	global_load_dwordx4 v[136:139], v6, s[78:79] offset:128
	global_load_dwordx4 v[140:143], v6, s[78:79] offset:192
	s_add_u32 s80, s4, 0x30d81000
	s_addc_u32 s81, s5, 0
	s_lshl_b32 s3, s30, 14
	s_add_u32 s80, s80, s3
	s_addc_u32 s81, s81, 0
	s_add_u32 s82, s80, 0x1000
	s_addc_u32 s83, s81, 0
	s_add_u32 s84, s80, 0x2000
	s_addc_u32 s85, s81, 0
	s_add_u32 s86, s80, 0x3000
	s_addc_u32 s87, s81, 0
	global_load_dwordx4 v[144:147], v6, s[80:81] offset:0
	global_load_dwordx4 v[148:151], v6, s[80:81] offset:64
	global_load_dwordx4 v[152:155], v6, s[80:81] offset:128
	global_load_dwordx4 v[156:159], v6, s[80:81] offset:192
	global_load_dwordx4 v[160:163], v6, s[82:83] offset:0
	global_load_dwordx4 v[164:167], v6, s[82:83] offset:64
	global_load_dwordx4 v[168:171], v6, s[82:83] offset:128
	global_load_dwordx4 v[172:175], v6, s[82:83] offset:192
	global_load_dwordx4 v[192:195], v6, s[84:85] offset:0
	global_load_dwordx4 v[196:199], v6, s[84:85] offset:64
	global_load_dwordx4 v[200:203], v6, s[84:85] offset:128
	global_load_dwordx4 v[204:207], v6, s[84:85] offset:192
	global_load_dwordx4 v[208:211], v6, s[86:87] offset:0
	global_load_dwordx4 v[212:215], v6, s[86:87] offset:64
	global_load_dwordx4 v[216:219], v6, s[86:87] offset:128
	global_load_dwordx4 v[220:223], v6, s[86:87] offset:192
	s_waitcnt vmcnt(36)
	s_add_u32 s88, s4, 0x2e501000
	s_addc_u32 s89, s5, 0
	s_lshl_b32 s3, s31, 14
	s_add_u32 s88, s88, s3
	s_addc_u32 s89, s89, 0
	s_add_u32 s90, s88, 0x1000
	s_addc_u32 s91, s89, 0
	s_add_u32 s92, s88, 0x2000
	s_addc_u32 s93, s89, 0
	s_add_u32 s94, s88, 0x3000
	s_addc_u32 s95, s89, 0
	v_mfma_f32_16x16x32_bf16 v[16:19], v[64:67], v[32:35], 0
	v_mfma_f32_16x16x32_bf16 v[20:23], v[64:67], v[40:43], 0
	v_mfma_f32_16x16x32_bf16 v[24:27], v[64:67], v[48:51], 0
	v_mfma_f32_16x16x32_bf16 v[28:31], v[64:67], v[56:59], 0
	v_mfma_f32_16x16x32_bf16 v[16:19], v[68:71], v[36:39], v[16:19]
	v_mfma_f32_16x16x32_bf16 v[20:23], v[68:71], v[44:47], v[20:23]
	v_mfma_f32_16x16x32_bf16 v[24:27], v[68:71], v[52:55], v[24:27]
	v_mfma_f32_16x16x32_bf16 v[28:31], v[68:71], v[60:63], v[28:31]
	s_nop 7
	s_nop 3
	v_cvt_pk_bf16_f32 v16, v16, v17
	v_cvt_pk_bf16_f32 v17, v18, v19
	v_cvt_pk_bf16_f32 v20, v20, v21
	v_cvt_pk_bf16_f32 v21, v22, v23
	v_cvt_pk_bf16_f32 v24, v24, v25
	v_cvt_pk_bf16_f32 v25, v26, v27
	v_cvt_pk_bf16_f32 v28, v28, v29
	v_cvt_pk_bf16_f32 v29, v30, v31
	global_store_dwordx2 v8, v[16:17], s[88:89] offset:0
	global_store_dwordx2 v8, v[20:21], s[90:91] offset:0
	global_store_dwordx2 v8, v[24:25], s[92:93] offset:0
	global_store_dwordx2 v8, v[28:29], s[94:95] offset:0
	s_nop 1
	v_mfma_f32_16x16x32_bf16 v[16:19], v[72:75], v[32:35], 0
	v_mfma_f32_16x16x32_bf16 v[20:23], v[72:75], v[40:43], 0
	v_mfma_f32_16x16x32_bf16 v[24:27], v[72:75], v[48:51], 0
	v_mfma_f32_16x16x32_bf16 v[28:31], v[72:75], v[56:59], 0
	v_mfma_f32_16x16x32_bf16 v[16:19], v[76:79], v[36:39], v[16:19]
	v_mfma_f32_16x16x32_bf16 v[20:23], v[76:79], v[44:47], v[20:23]
; __device__ __forceinline__ u32x2 pk4(f32x4 v) { u32x2 r; r.x = pk2(v[0], v[1]); r.y = pk2(v[2], v[3]); return r; }
; __device__ __forceinline__ f32x4 mfma16(bf16x8 a, bf16x8 b, f32x4 c) { return __builtin_amdgcn_mfma_f32_16x16x32_bf16(a, b, c, 0, 0, 0); }
; __device__ void ssd_s1(const Ctx& c, int ck, int h) {
;     ...
;     for (int nb = 0; nb < 8; ++nb) { bf16x8 bt[2];
; #pragma unroll
;         for (int kk = 0; kk < 2; ++kk) bt[kk] = ldfrag(sBT + ((size_t)(ck * 2 + g) * 128 + nb * 16 + r) * 64 + kk * 32 + q * 8);
; #pragma unroll
;         for (int pb = 0; pb < 4; ++pb) { f32x4 a = (f32x4){0.f, 0.f, 0.f, 0.f};
; #pragma unroll
;             for (int kk = 0; kk < 2; ++kk) a = mfma16(bt[kk], xw[pb][kk], a);
;             *(u32x2*)(sSt + (chh * 64 + pb * 16 + r) * 128 + nb * 16 + 4 * q) = pk4(a); } }
	v_mfma_f32_16x16x32_bf16 v[24:27], v[76:79], v[52:55], v[24:27]
	v_mfma_f32_16x16x32_bf16 v[28:31], v[76:79], v[60:63], v[28:31]
	s_nop 7
	s_nop 3
	v_cvt_pk_bf16_f32 v16, v16, v17
	v_cvt_pk_bf16_f32 v17, v18, v19
	v_cvt_pk_bf16_f32 v20, v20, v21
	v_cvt_pk_bf16_f32 v21, v22, v23
	v_cvt_pk_bf16_f32 v24, v24, v25
	v_cvt_pk_bf16_f32 v25, v26, v27
	v_cvt_pk_bf16_f32 v28, v28, v29
	v_cvt_pk_bf16_f32 v29, v30, v31
	global_store_dwordx2 v8, v[16:17], s[88:89] offset:32
	global_store_dwordx2 v8, v[20:21], s[90:91] offset:32
	global_store_dwordx2 v8, v[24:25], s[92:93] offset:32
	global_store_dwordx2 v8, v[28:29], s[94:95] offset:32
	s_nop 1
	v_mfma_f32_16x16x32_bf16 v[16:19], v[80:83], v[32:35], 0
	v_mfma_f32_16x16x32_bf16 v[20:23], v[80:83], v[40:43], 0
	v_mfma_f32_16x16x32_bf16 v[24:27], v[80:83], v[48:51], 0
	v_mfma_f32_16x16x32_bf16 v[28:31], v[80:83], v[56:59], 0
	v_mfma_f32_16x16x32_bf16 v[16:19], v[84:87], v[36:39], v[16:19]
	v_mfma_f32_16x16x32_bf16 v[20:23], v[84:87], v[44:47], v[20:23]
	v_mfma_f32_16x16x32_bf16 v[24:27], v[84:87], v[52:55], v[24:27]
	v_mfma_f32_16x16x32_bf16 v[28:31], v[84:87], v[60:63], v[28:31]
	s_nop 7
	s_nop 3
	v_cvt_pk_bf16_f32 v16, v16, v17
	v_cvt_pk_bf16_f32 v17, v18, v19
	v_cvt_pk_bf16_f32 v20, v20, v21
	v_cvt_pk_bf16_f32 v21, v22, v23
	v_cvt_pk_bf16_f32 v24, v24, v25
	v_cvt_pk_bf16_f32 v25, v26, v27
	v_cvt_pk_bf16_f32 v28, v28, v29
	v_cvt_pk_bf16_f32 v29, v30, v31
	global_store_dwordx2 v8, v[16:17], s[88:89] offset:64
	global_store_dwordx2 v8, v[20:21], s[90:91] offset:64
	global_store_dwordx2 v8, v[24:25], s[92:93] offset:64
	global_store_dwordx2 v8, v[28:29], s[94:95] offset:64
	s_nop 1
	v_mfma_f32_16x16x32_bf16 v[16:19], v[88:91], v[32:35], 0
	v_mfma_f32_16x16x32_bf16 v[20:23], v[88:91], v[40:43], 0
	v_mfma_f32_16x16x32_bf16 v[24:27], v[88:91], v[48:51], 0
	v_mfma_f32_16x16x32_bf16 v[28:31], v[88:91], v[56:59], 0
	v_mfma_f32_16x16x32_bf16 v[16:19], v[92:95], v[36:39], v[16:19]
	v_mfma_f32_16x16x32_bf16 v[20:23], v[92:95], v[44:47], v[20:23]
	v_mfma_f32_16x16x32_bf16 v[24:27], v[92:95], v[52:55], v[24:27]
	v_mfma_f32_16x16x32_bf16 v[28:31], v[92:95], v[60:63], v[28:31]
	s_nop 7
	s_nop 3
	v_cvt_pk_bf16_f32 v16, v16, v17
	v_cvt_pk_bf16_f32 v17, v18, v19
	v_cvt_pk_bf16_f32 v20, v20, v21
	v_cvt_pk_bf16_f32 v21, v22, v23
	v_cvt_pk_bf16_f32 v24, v24, v25
	v_cvt_pk_bf16_f32 v25, v26, v27
	v_cvt_pk_bf16_f32 v28, v28, v29
	v_cvt_pk_bf16_f32 v29, v30, v31
	global_store_dwordx2 v8, v[16:17], s[88:89] offset:96
	global_store_dwordx2 v8, v[20:21], s[90:91] offset:96
	global_store_dwordx2 v8, v[24:25], s[92:93] offset:96
	global_store_dwordx2 v8, v[28:29], s[94:95] offset:96
	s_nop 1
	v_mfma_f32_16x16x32_bf16 v[16:19], v[96:99], v[32:35], 0
	v_mfma_f32_16x16x32_bf16 v[20:23], v[96:99], v[40:43], 0
	v_mfma_f32_16x16x32_bf16 v[24:27], v[96:99], v[48:51], 0
	v_mfma_f32_16x16x32_bf16 v[28:31], v[96:99], v[56:59], 0
	v_mfma_f32_16x16x32_bf16 v[16:19], v[100:103], v[36:39], v[16:19]
	v_mfma_f32_16x16x32_bf16 v[20:23], v[100:103], v[44:47], v[20:23]
	v_mfma_f32_16x16x32_bf16 v[24:27], v[100:103], v[52:55], v[24:27]
	v_mfma_f32_16x16x32_bf16 v[28:31], v[100:103], v[60:63], v[28:31]
	s_nop 7
	s_nop 3
	v_cvt_pk_bf16_f32 v16, v16, v17
	v_cvt_pk_bf16_f32 v17, v18, v19
	v_cvt_pk_bf16_f32 v20, v20, v21
	v_cvt_pk_bf16_f32 v21, v22, v23
	v_cvt_pk_bf16_f32 v24, v24, v25
	v_cvt_pk_bf16_f32 v25, v26, v27
	v_cvt_pk_bf16_f32 v28, v28, v29
	v_cvt_pk_bf16_f32 v29, v30, v31
	global_store_dwordx2 v8, v[16:17], s[88:89] offset:128
	global_store_dwordx2 v8, v[20:21], s[90:91] offset:128
	global_store_dwordx2 v8, v[24:25], s[92:93] offset:128
	global_store_dwordx2 v8, v[28:29], s[94:95] offset:128
	s_nop 1
	v_mfma_f32_16x16x32_bf16 v[16:19], v[104:107], v[32:35], 0
	v_mfma_f32_16x16x32_bf16 v[20:23], v[104:107], v[40:43], 0
	v_mfma_f32_16x16x32_bf16 v[24:27], v[104:107], v[48:51], 0
	v_mfma_f32_16x16x32_bf16 v[28:31], v[104:107], v[56:59], 0
	v_mfma_f32_16x16x32_bf16 v[16:19], v[108:111], v[36:39], v[16:19]
	v_mfma_f32_16x16x32_bf16 v[20:23], v[108:111], v[44:47], v[20:23]
	v_mfma_f32_16x16x32_bf16 v[24:27], v[108:111], v[52:55], v[24:27]
	v_mfma_f32_16x16x32_bf16 v[28:31], v[108:111], v[60:63], v[28:31]
	s_nop 7
	s_nop 3
	v_cvt_pk_bf16_f32 v16, v16, v17
	v_cvt_pk_bf16_f32 v17, v18, v19
	v_cvt_pk_bf16_f32 v20, v20, v21
	v_cvt_pk_bf16_f32 v21, v22, v23
	v_cvt_pk_bf16_f32 v24, v24, v25
	v_cvt_pk_bf16_f32 v25, v26, v27
	v_cvt_pk_bf16_f32 v28, v28, v29
	v_cvt_pk_bf16_f32 v29, v30, v31
	global_store_dwordx2 v8, v[16:17], s[88:89] offset:160
	global_store_dwordx2 v8, v[20:21], s[90:91] offset:160
	global_store_dwordx2 v8, v[24:25], s[92:93] offset:160
	global_store_dwordx2 v8, v[28:29], s[94:95] offset:160
	s_nop 1
	v_mfma_f32_16x16x32_bf16 v[16:19], v[112:115], v[32:35], 0
	v_mfma_f32_16x16x32_bf16 v[20:23], v[112:115], v[40:43], 0
; __device__ __forceinline__ u32x2 pk4(f32x4 v) { u32x2 r; r.x = pk2(v[0], v[1]); r.y = pk2(v[2], v[3]); return r; }
; __device__ __forceinline__ f32x4 mfma16(bf16x8 a, bf16x8 b, f32x4 c) { return __builtin_amdgcn_mfma_f32_16x16x32_bf16(a, b, c, 0, 0, 0); }
;     template <class Tp> __device__ __forceinline__ Tp* W(size_t off) const { return (Tp*)(ws + off); }
; __device__ void gla_attn(const Ctx& c, int ck, int h, int ib) {
;     const bf16_t* gQg = c.W<bf16_t>(WS_GQG); const bf16_t* gKn = c.W<bf16_t>(WS_GKN); bf16_t* gAtt = c.W<bf16_t>(WS_GATT);
;     const int r = c.r, q = c.q; const size_t chh = (size_t)(ck * 4 + h); const int i = ib * 16 + r;
; #pragma unroll
;     for (int jb = 0; jb < 4; ++jb) { f32x4 a = (f32x4){0.f, 0.f, 0.f, 0.f};
;         if (jb <= ib) {
; #pragma unroll
;             for (int k0 = 0; k0 < 128; k0 += 32)
;                 a = mfma16(ldfrag(gKn + (chh * 64 + jb * 16 + r) * 128 + k0 + q * 8), ldfrag(gQg + (chh * 64 + i) * 128 + k0 + q * 8), a);
;         }
; #pragma unroll
;         for (int j = 0; j < 4; ++j) { const int jj = jb * 16 + 4 * q + j; if (jj > i) a[j] = 0.f; }
;         *(u32x2*)(gAtt + (chh * 64 + i) * 64 + jb * 16 + 4 * q) = pk4(a); }
; __device__ void gla_g1(const Ctx& c, int ck, int h, int vq) {
;     const bf16_t* gVT = c.W<bf16_t>(WS_GVT); const bf16_t* gKnT = c.W<bf16_t>(WS_GKNT); bf16_t* gSt = c.W<bf16_t>(WS_GST); const float* gDec = c.W<float>(WS_GDEC);
;     const int r = c.r, q = c.q; const size_t chh = (size_t)(ck * 4 + h);
;     bf16x8 vt[4][2];
; #pragma unroll
;     for (int vb = 0; vb < 4; ++vb)
; #pragma unroll
;         for (int kk = 0; kk < 2; ++kk) vt[vb][kk] = ldfrag(gVT + (chh * 256 + (vq * 4 + vb) * 16 + r) * 64 + kk * 32 + q * 8);
; #pragma unroll
;     for (int kb = 0; kb < 8; ++kb) { bf16x8 kt[2];
; #pragma unroll
;         for (int kk = 0; kk < 2; ++kk) kt[kk] = ldfrag(gKnT + (chh * 128 + kb * 16 + r) * 64 + kk * 32 + q * 8);
	v_mfma_f32_16x16x32_bf16 v[24:27], v[112:115], v[48:51], 0
	v_mfma_f32_16x16x32_bf16 v[28:31], v[112:115], v[56:59], 0
	v_mfma_f32_16x16x32_bf16 v[16:19], v[116:119], v[36:39], v[16:19]
	v_mfma_f32_16x16x32_bf16 v[20:23], v[116:119], v[44:47], v[20:23]
	v_mfma_f32_16x16x32_bf16 v[24:27], v[116:119], v[52:55], v[24:27]
	v_mfma_f32_16x16x32_bf16 v[28:31], v[116:119], v[60:63], v[28:31]
	s_nop 7
	s_nop 3
	v_cvt_pk_bf16_f32 v16, v16, v17
	v_cvt_pk_bf16_f32 v17, v18, v19
	v_cvt_pk_bf16_f32 v20, v20, v21
	v_cvt_pk_bf16_f32 v21, v22, v23
	v_cvt_pk_bf16_f32 v24, v24, v25
	v_cvt_pk_bf16_f32 v25, v26, v27
	v_cvt_pk_bf16_f32 v28, v28, v29
	v_cvt_pk_bf16_f32 v29, v30, v31
	global_store_dwordx2 v8, v[16:17], s[88:89] offset:192
	global_store_dwordx2 v8, v[20:21], s[90:91] offset:192
	global_store_dwordx2 v8, v[24:25], s[92:93] offset:192
	global_store_dwordx2 v8, v[28:29], s[94:95] offset:192
	s_nop 1
	v_mfma_f32_16x16x32_bf16 v[16:19], v[120:123], v[32:35], 0
	v_mfma_f32_16x16x32_bf16 v[20:23], v[120:123], v[40:43], 0
	v_mfma_f32_16x16x32_bf16 v[24:27], v[120:123], v[48:51], 0
	v_mfma_f32_16x16x32_bf16 v[28:31], v[120:123], v[56:59], 0
	v_mfma_f32_16x16x32_bf16 v[16:19], v[124:127], v[36:39], v[16:19]
	v_mfma_f32_16x16x32_bf16 v[20:23], v[124:127], v[44:47], v[20:23]
	v_mfma_f32_16x16x32_bf16 v[24:27], v[124:127], v[52:55], v[24:27]
	v_mfma_f32_16x16x32_bf16 v[28:31], v[124:127], v[60:63], v[28:31]
	s_nop 7
	s_nop 3
	v_cvt_pk_bf16_f32 v16, v16, v17
	v_cvt_pk_bf16_f32 v17, v18, v19
	v_cvt_pk_bf16_f32 v20, v20, v21
	v_cvt_pk_bf16_f32 v21, v22, v23
	v_cvt_pk_bf16_f32 v24, v24, v25
	v_cvt_pk_bf16_f32 v25, v26, v27
	v_cvt_pk_bf16_f32 v28, v28, v29
	v_cvt_pk_bf16_f32 v29, v30, v31
	global_store_dwordx2 v8, v[16:17], s[88:89] offset:224
	global_store_dwordx2 v8, v[20:21], s[90:91] offset:224
	global_store_dwordx2 v8, v[24:25], s[92:93] offset:224
	global_store_dwordx2 v8, v[28:29], s[94:95] offset:224
	s_nop 1
	s_add_u32 s96, s4, 0x31d81000
	s_addc_u32 s97, s5, 0
	s_lshl_b32 s3, s30, 15
	s_add_u32 s96, s96, s3
	s_addc_u32 s97, s97, 0
	s_lshl_b32 s3, s10, 13
	s_add_u32 s96, s96, s3
	s_addc_u32 s97, s97, 0
	s_add_u32 s98, s96, 0x1000
	s_addc_u32 s99, s97, 0
	global_load_dwordx4 v[32:35], v5, s[96:97] offset:0
	global_load_dwordx4 v[36:39], v5, s[96:97] offset:64
	global_load_dwordx4 v[40:43], v5, s[96:97] offset:2048
	global_load_dwordx4 v[44:47], v5, s[96:97] offset:2112
	global_load_dwordx4 v[48:51], v5, s[98:99] offset:0
	global_load_dwordx4 v[52:55], v5, s[98:99] offset:64
	global_load_dwordx4 v[56:59], v5, s[98:99] offset:2048
	global_load_dwordx4 v[60:63], v5, s[98:99] offset:2112
	s_add_u32 s12, s4, 0x31581000
	s_addc_u32 s13, s5, 0
	s_lshl_b32 s3, s30, 14
	s_add_u32 s12, s12, s3
	s_addc_u32 s13, s13, 0
	s_add_u32 s14, s12, 0x1000
	s_addc_u32 s15, s13, 0
	s_add_u32 s16, s12, 0x2000
	s_addc_u32 s17, s13, 0
	s_add_u32 s18, s12, 0x3000
	s_addc_u32 s19, s13, 0
	global_load_dwordx4 v[64:67], v5, s[12:13] offset:0
	global_load_dwordx4 v[68:71], v5, s[12:13] offset:64
	global_load_dwordx4 v[72:75], v5, s[12:13] offset:2048
	global_load_dwordx4 v[76:79], v5, s[12:13] offset:2112
	global_load_dwordx4 v[80:83], v5, s[14:15] offset:0
	global_load_dwordx4 v[84:87], v5, s[14:15] offset:64
	global_load_dwordx4 v[88:91], v5, s[14:15] offset:2048
	global_load_dwordx4 v[92:95], v5, s[14:15] offset:2112
	global_load_dwordx4 v[96:99], v5, s[16:17] offset:0
	global_load_dwordx4 v[100:103], v5, s[16:17] offset:64
	global_load_dwordx4 v[104:107], v5, s[16:17] offset:2048
	global_load_dwordx4 v[108:111], v5, s[16:17] offset:2112
	global_load_dwordx4 v[112:115], v5, s[18:19] offset:0
	global_load_dwordx4 v[116:119], v5, s[18:19] offset:64
	global_load_dwordx4 v[120:123], v5, s[18:19] offset:2048
	global_load_dwordx4 v[124:127], v5, s[18:19] offset:2112
	s_waitcnt vmcnt(56)
	s_add_u32 s20, s4, 0x32d81000
	s_addc_u32 s21, s5, 0
	s_lshl_b32 s3, s30, 13
	s_add_u32 s20, s20, s3
	s_addc_u32 s21, s21, 0
	s_lshl_b32 s3, s10, 11
	s_add_u32 s20, s20, s3
	s_addc_u32 s21, s21, 0
	v_add_u32_e32 v14, 0, v11
	v_cmp_le_u32_e64 s[32:33], v14, v1
	v_add_u32_e32 v14, 1, v11
	v_cmp_le_u32_e64 s[34:35], v14, v1
	v_add_u32_e32 v14, 2, v11
	v_cmp_le_u32_e64 s[36:37], v14, v1
	v_add_u32_e32 v14, 3, v11
	v_cmp_le_u32_e64 s[38:39], v14, v1
	s_cmp_lt_u32 s10, 0
	s_cbranch_scc1 .Lmt_c_zero0
	v_mfma_f32_16x16x32_bf16 v[16:19], v[144:147], v[128:131], 0
	v_mfma_f32_16x16x32_bf16 v[16:19], v[148:151], v[132:135], v[16:19]
	v_mfma_f32_16x16x32_bf16 v[16:19], v[152:155], v[136:139], v[16:19]
	v_mfma_f32_16x16x32_bf16 v[16:19], v[156:159], v[140:143], v[16:19]
	s_cmp_eq_u32 s10, 0
	s_cbranch_scc0 .Lmt_c_done0
	s_nop 7
	s_nop 3
	v_cndmask_b32_e64 v16, 0, v16, s[32:33]
	v_cndmask_b32_e64 v17, 0, v17, s[34:35]
	v_cndmask_b32_e64 v18, 0, v18, s[36:37]
	v_cndmask_b32_e64 v19, 0, v19, s[38:39]
	s_branch .Lmt_c_done0

; __device__ __forceinline__ u32x2 pk4(f32x4 v) { u32x2 r; r.x = pk2(v[0], v[1]); r.y = pk2(v[2], v[3]); return r; }
; __device__ __forceinline__ f32x4 mfma16(bf16x8 a, bf16x8 b, f32x4 c) { return __builtin_amdgcn_mfma_f32_16x16x32_bf16(a, b, c, 0, 0, 0); }
; __device__ void gla_attn(const Ctx& c, int ck, int h, int ib) {
;     ...
; #pragma unroll
;         for (int j = 0; j < 4; ++j) { const int jj = jb * 16 + 4 * q + j; if (jj > i) a[j] = 0.f; }
;         *(u32x2*)(gAtt + (chh * 64 + i) * 64 + jb * 16 + 4 * q) = pk4(a); }
; __device__ void gla_g1(const Ctx& c, int ck, int h, int vq) {
;     ...
;     for (int kb = 0; kb < 8; ++kb) { bf16x8 kt[2];
; #pragma unroll
;         for (int kk = 0; kk < 2; ++kk) kt[kk] = ldfrag(gKnT + (chh * 128 + kb * 16 + r) * 64 + kk * 32 + q * 8);
;         const f32x4 d = *(const f32x4*)(gDec + (size_t)ck * 512 + h * 128 + kb * 16 + 4 * q);
; #pragma unroll
;         for (int vb = 0; vb < 4; ++vb) { f32x4 a = (f32x4){0.f, 0.f, 0.f, 0.f};
; #pragma unroll
;             for (int kk = 0; kk < 2; ++kk) a = mfma16(kt[kk], vt[vb][kk], a);
;             a = a * d;
;             *(u32x2*)(gSt + (chh * 256 + (vq * 4 + vb) * 16 + r) * 128 + kb * 16 + 4 * q) = pk4(a); } }
.Lmt_c_done3:
	s_nop 7
	s_nop 3
	v_cvt_pk_bf16_f32 v16, v16, v17
	v_cvt_pk_bf16_f32 v17, v18, v19
	v_cvt_pk_bf16_f32 v20, v20, v21
	v_cvt_pk_bf16_f32 v21, v22, v23
	v_cvt_pk_bf16_f32 v24, v24, v25
	v_cvt_pk_bf16_f32 v25, v26, v27
	v_cvt_pk_bf16_f32 v28, v28, v29
	v_cvt_pk_bf16_f32 v29, v30, v31
	global_store_dwordx2 v9, v[16:17], s[20:21] offset:0
	global_store_dwordx2 v9, v[20:21], s[20:21] offset:32
	global_store_dwordx2 v9, v[24:25], s[20:21] offset:64
	global_store_dwordx2 v9, v[28:29], s[20:21] offset:96
	s_nop 1
	s_add_u32 s22, s4, 0x35181000
	s_addc_u32 s23, s5, 0
	s_lshl_b32 s3, s7, 11
	s_add_u32 s22, s22, s3
	s_addc_u32 s23, s23, 0
	s_lshl_b32 s3, s8, 10
	s_add_u32 s22, s22, s3
	s_addc_u32 s23, s23, 0
	s_lshl_b32 s3, s11, 9
	s_add_u32 s22, s22, s3
	s_addc_u32 s23, s23, 0
	global_load_dwordx4 v[128:131], v3, s[22:23] offset:0
	global_load_dwordx4 v[132:135], v3, s[22:23] offset:64
	global_load_dwordx4 v[136:139], v3, s[22:23] offset:128
	global_load_dwordx4 v[140:143], v3, s[22:23] offset:192
	global_load_dwordx4 v[144:147], v3, s[22:23] offset:256
	global_load_dwordx4 v[148:151], v3, s[22:23] offset:320
	global_load_dwordx4 v[152:155], v3, s[22:23] offset:384
	global_load_dwordx4 v[156:159], v3, s[22:23] offset:448
	s_waitcnt vmcnt(12)
	s_add_u32 s24, s4, 0x33181000
	s_addc_u32 s25, s5, 0
	s_lshl_b32 s3, s30, 16
	s_add_u32 s24, s24, s3
	s_addc_u32 s25, s25, 0
	s_lshl_b32 s3, s10, 14
	s_add_u32 s24, s24, s3
	s_addc_u32 s25, s25, 0
	s_add_u32 s26, s24, 0x1000
	s_addc_u32 s27, s25, 0
	s_add_u32 s28, s24, 0x2000
	s_addc_u32 s29, s25, 0
	s_add_u32 s64, s24, 0x3000
	s_addc_u32 s65, s25, 0
	v_mfma_f32_16x16x32_bf16 v[16:19], v[64:67], v[32:35], 0
	v_mfma_f32_16x16x32_bf16 v[20:23], v[64:67], v[40:43], 0
	v_mfma_f32_16x16x32_bf16 v[24:27], v[64:67], v[48:51], 0
	v_mfma_f32_16x16x32_bf16 v[28:31], v[64:67], v[56:59], 0
	v_mfma_f32_16x16x32_bf16 v[16:19], v[68:71], v[36:39], v[16:19]
	v_mfma_f32_16x16x32_bf16 v[20:23], v[68:71], v[44:47], v[20:23]
	v_mfma_f32_16x16x32_bf16 v[24:27], v[68:71], v[52:55], v[24:27]
	v_mfma_f32_16x16x32_bf16 v[28:31], v[68:71], v[60:63], v[28:31]
	s_waitcnt vmcnt(0)
	s_nop 7
	s_nop 3
	v_mul_f32_e32 v16, v16, v128
	v_mul_f32_e32 v17, v17, v129
	v_mul_f32_e32 v18, v18, v130
	v_mul_f32_e32 v19, v19, v131
	v_mul_f32_e32 v20, v20, v128
	v_mul_f32_e32 v21, v21, v129
	v_mul_f32_e32 v22, v22, v130
	v_mul_f32_e32 v23, v23, v131
	v_mul_f32_e32 v24, v24, v128
	v_mul_f32_e32 v25, v25, v129
	v_mul_f32_e32 v26, v26, v130
	v_mul_f32_e32 v27, v27, v131
	v_mul_f32_e32 v28, v28, v128
	v_mul_f32_e32 v29, v29, v129
	v_mul_f32_e32 v30, v30, v130
	v_mul_f32_e32 v31, v31, v131
	v_cvt_pk_bf16_f32 v16, v16, v17
	v_cvt_pk_bf16_f32 v17, v18, v19
	v_cvt_pk_bf16_f32 v20, v20, v21
	v_cvt_pk_bf16_f32 v21, v22, v23
	v_cvt_pk_bf16_f32 v24, v24, v25
	v_cvt_pk_bf16_f32 v25, v26, v27
	v_cvt_pk_bf16_f32 v28, v28, v29
	v_cvt_pk_bf16_f32 v29, v30, v31
	global_store_dwordx2 v8, v[16:17], s[24:25] offset:0
	global_store_dwordx2 v8, v[20:21], s[26:27] offset:0
	global_store_dwordx2 v8, v[24:25], s[28:29] offset:0
	global_store_dwordx2 v8, v[28:29], s[64:65] offset:0
	s_nop 1
	v_mfma_f32_16x16x32_bf16 v[16:19], v[72:75], v[32:35], 0
	v_mfma_f32_16x16x32_bf16 v[20:23], v[72:75], v[40:43], 0
	v_mfma_f32_16x16x32_bf16 v[24:27], v[72:75], v[48:51], 0
	v_mfma_f32_16x16x32_bf16 v[28:31], v[72:75], v[56:59], 0
	v_mfma_f32_16x16x32_bf16 v[16:19], v[76:79], v[36:39], v[16:19]
	v_mfma_f32_16x16x32_bf16 v[20:23], v[76:79], v[44:47], v[20:23]
	v_mfma_f32_16x16x32_bf16 v[24:27], v[76:79], v[52:55], v[24:27]
	v_mfma_f32_16x16x32_bf16 v[28:31], v[76:79], v[60:63], v[28:31]
	s_nop 7
	s_nop 3
	v_mul_f32_e32 v16, v16, v132
	v_mul_f32_e32 v17, v17, v133
	v_mul_f32_e32 v18, v18, v134
	v_mul_f32_e32 v19, v19, v135
	v_mul_f32_e32 v20, v20, v132
	v_mul_f32_e32 v21, v21, v133
	v_mul_f32_e32 v22, v22, v134
	v_mul_f32_e32 v23, v23, v135
	v_mul_f32_e32 v24, v24, v132
	v_mul_f32_e32 v25, v25, v133
	v_mul_f32_e32 v26, v26, v134
	v_mul_f32_e32 v27, v27, v135
	v_mul_f32_e32 v28, v28, v132
	v_mul_f32_e32 v29, v29, v133
	v_mul_f32_e32 v30, v30, v134
	v_mul_f32_e32 v31, v31, v135
	v_cvt_pk_bf16_f32 v16, v16, v17
	v_cvt_pk_bf16_f32 v17, v18, v19
	v_cvt_pk_bf16_f32 v20, v20, v21
	v_cvt_pk_bf16_f32 v21, v22, v23
	v_cvt_pk_bf16_f32 v24, v24, v25
	v_cvt_pk_bf16_f32 v25, v26, v27
	v_cvt_pk_bf16_f32 v28, v28, v29
	v_cvt_pk_bf16_f32 v29, v30, v31
	global_store_dwordx2 v8, v[16:17], s[24:25] offset:32
	global_store_dwordx2 v8, v[20:21], s[26:27] offset:32
	global_store_dwordx2 v8, v[24:25], s[28:29] offset:32
	global_store_dwordx2 v8, v[28:29], s[64:65] offset:32
	s_nop 1
	v_mfma_f32_16x16x32_bf16 v[16:19], v[80:83], v[32:35], 0
	v_mfma_f32_16x16x32_bf16 v[20:23], v[80:83], v[40:43], 0
	v_mfma_f32_16x16x32_bf16 v[24:27], v[80:83], v[48:51], 0
	v_mfma_f32_16x16x32_bf16 v[28:31], v[80:83], v[56:59], 0
	v_mfma_f32_16x16x32_bf16 v[16:19], v[84:87], v[36:39], v[16:19]
	v_mfma_f32_16x16x32_bf16 v[20:23], v[84:87], v[44:47], v[20:23]
	v_mfma_f32_16x16x32_bf16 v[24:27], v[84:87], v[52:55], v[24:27]
	v_mfma_f32_16x16x32_bf16 v[28:31], v[84:87], v[60:63], v[28:31]
	s_nop 7
	s_nop 3
	v_mul_f32_e32 v16, v16, v136
	v_mul_f32_e32 v17, v17, v137
	v_mul_f32_e32 v18, v18, v138
	v_mul_f32_e32 v19, v19, v139
	v_mul_f32_e32 v20, v20, v136
	v_mul_f32_e32 v21, v21, v137
	v_mul_f32_e32 v22, v22, v138
	v_mul_f32_e32 v23, v23, v139
	v_mul_f32_e32 v24, v24, v136
	v_mul_f32_e32 v25, v25, v137
	v_mul_f32_e32 v26, v26, v138
	v_mul_f32_e32 v27, v27, v139
	v_mul_f32_e32 v28, v28, v136
	v_mul_f32_e32 v29, v29, v137
	v_mul_f32_e32 v30, v30, v138
	v_mul_f32_e32 v31, v31, v139
	v_cvt_pk_bf16_f32 v16, v16, v17
; __device__ __forceinline__ u32x2 pk4(f32x4 v) { u32x2 r; r.x = pk2(v[0], v[1]); r.y = pk2(v[2], v[3]); return r; }
; __device__ __forceinline__ f32x4 mfma16(bf16x8 a, bf16x8 b, f32x4 c) { return __builtin_amdgcn_mfma_f32_16x16x32_bf16(a, b, c, 0, 0, 0); }
; __device__ void gla_g1(const Ctx& c, int ck, int h, int vq) {
;     ...
;     for (int kb = 0; kb < 8; ++kb) { bf16x8 kt[2];
; #pragma unroll
;         for (int kk = 0; kk < 2; ++kk) kt[kk] = ldfrag(gKnT + (chh * 128 + kb * 16 + r) * 64 + kk * 32 + q * 8);
;         const f32x4 d = *(const f32x4*)(gDec + (size_t)ck * 512 + h * 128 + kb * 16 + 4 * q);
; #pragma unroll
;         for (int vb = 0; vb < 4; ++vb) { f32x4 a = (f32x4){0.f, 0.f, 0.f, 0.f};
; #pragma unroll
;             for (int kk = 0; kk < 2; ++kk) a = mfma16(kt[kk], vt[vb][kk], a);
;             a = a * d;
;             *(u32x2*)(gSt + (chh * 256 + (vq * 4 + vb) * 16 + r) * 128 + kb * 16 + 4 * q) = pk4(a); } }
	v_cvt_pk_bf16_f32 v17, v18, v19
	v_cvt_pk_bf16_f32 v20, v20, v21
	v_cvt_pk_bf16_f32 v21, v22, v23
	v_cvt_pk_bf16_f32 v24, v24, v25
	v_cvt_pk_bf16_f32 v25, v26, v27
	v_cvt_pk_bf16_f32 v28, v28, v29
	v_cvt_pk_bf16_f32 v29, v30, v31
	global_store_dwordx2 v8, v[16:17], s[24:25] offset:64
	global_store_dwordx2 v8, v[20:21], s[26:27] offset:64
	global_store_dwordx2 v8, v[24:25], s[28:29] offset:64
	global_store_dwordx2 v8, v[28:29], s[64:65] offset:64
	s_nop 1
	v_mfma_f32_16x16x32_bf16 v[16:19], v[88:91], v[32:35], 0
	v_mfma_f32_16x16x32_bf16 v[20:23], v[88:91], v[40:43], 0
	v_mfma_f32_16x16x32_bf16 v[24:27], v[88:91], v[48:51], 0
	v_mfma_f32_16x16x32_bf16 v[28:31], v[88:91], v[56:59], 0
	v_mfma_f32_16x16x32_bf16 v[16:19], v[92:95], v[36:39], v[16:19]
	v_mfma_f32_16x16x32_bf16 v[20:23], v[92:95], v[44:47], v[20:23]
	v_mfma_f32_16x16x32_bf16 v[24:27], v[92:95], v[52:55], v[24:27]
	v_mfma_f32_16x16x32_bf16 v[28:31], v[92:95], v[60:63], v[28:31]
	s_nop 7
	s_nop 3
	v_mul_f32_e32 v16, v16, v140
	v_mul_f32_e32 v17, v17, v141
	v_mul_f32_e32 v18, v18, v142
	v_mul_f32_e32 v19, v19, v143
	v_mul_f32_e32 v20, v20, v140
	v_mul_f32_e32 v21, v21, v141
	v_mul_f32_e32 v22, v22, v142
	v_mul_f32_e32 v23, v23, v143
	v_mul_f32_e32 v24, v24, v140
	v_mul_f32_e32 v25, v25, v141
	v_mul_f32_e32 v26, v26, v142
	v_mul_f32_e32 v27, v27, v143
	v_mul_f32_e32 v28, v28, v140
	v_mul_f32_e32 v29, v29, v141
	v_mul_f32_e32 v30, v30, v142
	v_mul_f32_e32 v31, v31, v143
	v_cvt_pk_bf16_f32 v16, v16, v17
	v_cvt_pk_bf16_f32 v17, v18, v19
	v_cvt_pk_bf16_f32 v20, v20, v21
	v_cvt_pk_bf16_f32 v21, v22, v23
	v_cvt_pk_bf16_f32 v24, v24, v25
	v_cvt_pk_bf16_f32 v25, v26, v27
	v_cvt_pk_bf16_f32 v28, v28, v29
	v_cvt_pk_bf16_f32 v29, v30, v31
	global_store_dwordx2 v8, v[16:17], s[24:25] offset:96
	global_store_dwordx2 v8, v[20:21], s[26:27] offset:96
	global_store_dwordx2 v8, v[24:25], s[28:29] offset:96
	global_store_dwordx2 v8, v[28:29], s[64:65] offset:96
	s_nop 1
	v_mfma_f32_16x16x32_bf16 v[16:19], v[96:99], v[32:35], 0
	v_mfma_f32_16x16x32_bf16 v[20:23], v[96:99], v[40:43], 0
	v_mfma_f32_16x16x32_bf16 v[24:27], v[96:99], v[48:51], 0
	v_mfma_f32_16x16x32_bf16 v[28:31], v[96:99], v[56:59], 0
	v_mfma_f32_16x16x32_bf16 v[16:19], v[100:103], v[36:39], v[16:19]
	v_mfma_f32_16x16x32_bf16 v[20:23], v[100:103], v[44:47], v[20:23]
	v_mfma_f32_16x16x32_bf16 v[24:27], v[100:103], v[52:55], v[24:27]
	v_mfma_f32_16x16x32_bf16 v[28:31], v[100:103], v[60:63], v[28:31]
	s_nop 7
	s_nop 3
	v_mul_f32_e32 v16, v16, v144
	v_mul_f32_e32 v17, v17, v145
	v_mul_f32_e32 v18, v18, v146
	v_mul_f32_e32 v19, v19, v147
	v_mul_f32_e32 v20, v20, v144
	v_mul_f32_e32 v21, v21, v145
	v_mul_f32_e32 v22, v22, v146
	v_mul_f32_e32 v23, v23, v147
	v_mul_f32_e32 v24, v24, v144
	v_mul_f32_e32 v25, v25, v145
	v_mul_f32_e32 v26, v26, v146
	v_mul_f32_e32 v27, v27, v147
	v_mul_f32_e32 v28, v28, v144
	v_mul_f32_e32 v29, v29, v145
	v_mul_f32_e32 v30, v30, v146
	v_mul_f32_e32 v31, v31, v147
	v_cvt_pk_bf16_f32 v16, v16, v17
	v_cvt_pk_bf16_f32 v17, v18, v19
	v_cvt_pk_bf16_f32 v20, v20, v21
	v_cvt_pk_bf16_f32 v21, v22, v23
	v_cvt_pk_bf16_f32 v24, v24, v25
	v_cvt_pk_bf16_f32 v25, v26, v27
	v_cvt_pk_bf16_f32 v28, v28, v29
	v_cvt_pk_bf16_f32 v29, v30, v31
	global_store_dwordx2 v8, v[16:17], s[24:25] offset:128
	global_store_dwordx2 v8, v[20:21], s[26:27] offset:128
	global_store_dwordx2 v8, v[24:25], s[28:29] offset:128
	global_store_dwordx2 v8, v[28:29], s[64:65] offset:128
	s_nop 1
	v_mfma_f32_16x16x32_bf16 v[16:19], v[104:107], v[32:35], 0
	v_mfma_f32_16x16x32_bf16 v[20:23], v[104:107], v[40:43], 0
	v_mfma_f32_16x16x32_bf16 v[24:27], v[104:107], v[48:51], 0
	v_mfma_f32_16x16x32_bf16 v[28:31], v[104:107], v[56:59], 0
	v_mfma_f32_16x16x32_bf16 v[16:19], v[108:111], v[36:39], v[16:19]
	v_mfma_f32_16x16x32_bf16 v[20:23], v[108:111], v[44:47], v[20:23]
	v_mfma_f32_16x16x32_bf16 v[24:27], v[108:111], v[52:55], v[24:27]
	v_mfma_f32_16x16x32_bf16 v[28:31], v[108:111], v[60:63], v[28:31]
	s_nop 7
	s_nop 3
	v_mul_f32_e32 v16, v16, v148
	v_mul_f32_e32 v17, v17, v149
	v_mul_f32_e32 v18, v18, v150
	v_mul_f32_e32 v19, v19, v151
	v_mul_f32_e32 v20, v20, v148
	v_mul_f32_e32 v21, v21, v149
	v_mul_f32_e32 v22, v22, v150
	v_mul_f32_e32 v23, v23, v151
	v_mul_f32_e32 v24, v24, v148
	v_mul_f32_e32 v25, v25, v149
	v_mul_f32_e32 v26, v26, v150
	v_mul_f32_e32 v27, v27, v151
	v_mul_f32_e32 v28, v28, v148
	v_mul_f32_e32 v29, v29, v149
	v_mul_f32_e32 v30, v30, v150
	v_mul_f32_e32 v31, v31, v151
	v_cvt_pk_bf16_f32 v16, v16, v17
	v_cvt_pk_bf16_f32 v17, v18, v19
	v_cvt_pk_bf16_f32 v20, v20, v21
	v_cvt_pk_bf16_f32 v21, v22, v23
	v_cvt_pk_bf16_f32 v24, v24, v25
	v_cvt_pk_bf16_f32 v25, v26, v27
	v_cvt_pk_bf16_f32 v28, v28, v29
	v_cvt_pk_bf16_f32 v29, v30, v31
	global_store_dwordx2 v8, v[16:17], s[24:25] offset:160
	global_store_dwordx2 v8, v[20:21], s[26:27] offset:160
	global_store_dwordx2 v8, v[24:25], s[28:29] offset:160
	global_store_dwordx2 v8, v[28:29], s[64:65] offset:160
	s_nop 1
	v_mfma_f32_16x16x32_bf16 v[16:19], v[112:115], v[32:35], 0
	v_mfma_f32_16x16x32_bf16 v[20:23], v[112:115], v[40:43], 0
	v_mfma_f32_16x16x32_bf16 v[24:27], v[112:115], v[48:51], 0
	v_mfma_f32_16x16x32_bf16 v[28:31], v[112:115], v[56:59], 0
	v_mfma_f32_16x16x32_bf16 v[16:19], v[116:119], v[36:39], v[16:19]
	v_mfma_f32_16x16x32_bf16 v[20:23], v[116:119], v[44:47], v[20:23]
	v_mfma_f32_16x16x32_bf16 v[24:27], v[116:119], v[52:55], v[24:27]
	v_mfma_f32_16x16x32_bf16 v[28:31], v[116:119], v[60:63], v[28:31]
	s_nop 7
	s_nop 3
	v_mul_f32_e32 v16, v16, v152
	v_mul_f32_e32 v17, v17, v153
	v_mul_f32_e32 v18, v18, v154
	v_mul_f32_e32 v19, v19, v155
	v_mul_f32_e32 v20, v20, v152
	v_mul_f32_e32 v21, v21, v153
; __device__ __forceinline__ u32x2 pk4(f32x4 v) { u32x2 r; r.x = pk2(v[0], v[1]); r.y = pk2(v[2], v[3]); return r; }
; __device__ __forceinline__ f32x4 mfma16(bf16x8 a, bf16x8 b, f32x4 c) { return __builtin_amdgcn_mfma_f32_16x16x32_bf16(a, b, c, 0, 0, 0); }
;     template <class Tp> __device__ __forceinline__ Tp* W(size_t off) const { return (Tp*)(ws + off); }
; __device__ void prep_dn_chunk(const Ctx& c, int ck, int half) {
;     const bf16_t* proj = c.W<bf16_t>(WS_PROJ);
;     const float* cw = c.in(I_DNCONV) + (size_t)c.layer * 4 * 3072;
;     bf16_t* dq = c.W<bf16_t>(WS_DQ); bf16_t* dk = c.W<bf16_t>(WS_DK); bf16_t* dv = c.W<bf16_t>(WS_DV);
;     for (int it = c.tid; it < 64 * 192; it += 1024) {
;         u32x4 r0[4], r1[4]; int t0, c0, t1, c1;
;         { const int l = it / 192, j = it - l * 192; t0 = ck * 64 + l; c0 = (j >> 6) * 1024 + half * 512 + (j & 63) * 8; }
;         { const int i2 = it + 512, l = i2 / 192, j = i2 - l * 192; t1 = ck * 64 + l; c1 = (j >> 6) * 1024 + half * 512 + (j & 63) * 8; }
;         prep_dn_load(proj, cw, -1, r0, t0, c0);
;         prep_dn_load(proj, cw, -1, r1, t1, c1);
;         prep_dn_finish(cw, dq, dk, dv, r0, t0, c0);
;         prep_dn_finish(cw, dq, dk, dv, r1, t1, c1);
;     }
; __device__ void gla_g1(const Ctx& c, int ck, int h, int vq) {
;     ...
;     for (int kb = 0; kb < 8; ++kb) { bf16x8 kt[2];
; #pragma unroll
;         for (int kk = 0; kk < 2; ++kk) kt[kk] = ldfrag(gKnT + (chh * 128 + kb * 16 + r) * 64 + kk * 32 + q * 8);
;         const f32x4 d = *(const f32x4*)(gDec + (size_t)ck * 512 + h * 128 + kb * 16 + 4 * q);
; #pragma unroll
;         for (int vb = 0; vb < 4; ++vb) { f32x4 a = (f32x4){0.f, 0.f, 0.f, 0.f};
; #pragma unroll
;             for (int kk = 0; kk < 2; ++kk) a = mfma16(kt[kk], vt[vb][kk], a);
;             a = a * d;
;             *(u32x2*)(gSt + (chh * 256 + (vq * 4 + vb) * 16 + r) * 128 + kb * 16 + 4 * q) = pk4(a); } }
	v_mul_f32_e32 v22, v22, v154
	v_mul_f32_e32 v23, v23, v155
	v_mul_f32_e32 v24, v24, v152
	v_mul_f32_e32 v25, v25, v153
	v_mul_f32_e32 v26, v26, v154
	v_mul_f32_e32 v27, v27, v155
	v_mul_f32_e32 v28, v28, v152
	v_mul_f32_e32 v29, v29, v153
	v_mul_f32_e32 v30, v30, v154
	v_mul_f32_e32 v31, v31, v155
	v_cvt_pk_bf16_f32 v16, v16, v17
	v_cvt_pk_bf16_f32 v17, v18, v19
	v_cvt_pk_bf16_f32 v20, v20, v21
	v_cvt_pk_bf16_f32 v21, v22, v23
	v_cvt_pk_bf16_f32 v24, v24, v25
	v_cvt_pk_bf16_f32 v25, v26, v27
	v_cvt_pk_bf16_f32 v28, v28, v29
	v_cvt_pk_bf16_f32 v29, v30, v31
	global_store_dwordx2 v8, v[16:17], s[24:25] offset:192
	global_store_dwordx2 v8, v[20:21], s[26:27] offset:192
	global_store_dwordx2 v8, v[24:25], s[28:29] offset:192
	global_store_dwordx2 v8, v[28:29], s[64:65] offset:192
	s_nop 1
	v_mfma_f32_16x16x32_bf16 v[16:19], v[120:123], v[32:35], 0
	v_mfma_f32_16x16x32_bf16 v[20:23], v[120:123], v[40:43], 0
	v_mfma_f32_16x16x32_bf16 v[24:27], v[120:123], v[48:51], 0
	v_mfma_f32_16x16x32_bf16 v[28:31], v[120:123], v[56:59], 0
	v_mfma_f32_16x16x32_bf16 v[16:19], v[124:127], v[36:39], v[16:19]
	v_mfma_f32_16x16x32_bf16 v[20:23], v[124:127], v[44:47], v[20:23]
	v_mfma_f32_16x16x32_bf16 v[24:27], v[124:127], v[52:55], v[24:27]
	v_mfma_f32_16x16x32_bf16 v[28:31], v[124:127], v[60:63], v[28:31]
	s_nop 7
	s_nop 3
	v_mul_f32_e32 v16, v16, v156
	v_mul_f32_e32 v17, v17, v157
	v_mul_f32_e32 v18, v18, v158
	v_mul_f32_e32 v19, v19, v159
	v_mul_f32_e32 v20, v20, v156
	v_mul_f32_e32 v21, v21, v157
	v_mul_f32_e32 v22, v22, v158
	v_mul_f32_e32 v23, v23, v159
	v_mul_f32_e32 v24, v24, v156
	v_mul_f32_e32 v25, v25, v157
	v_mul_f32_e32 v26, v26, v158
	v_mul_f32_e32 v27, v27, v159
	v_mul_f32_e32 v28, v28, v156
	v_mul_f32_e32 v29, v29, v157
	v_mul_f32_e32 v30, v30, v158
	v_mul_f32_e32 v31, v31, v159
	v_cvt_pk_bf16_f32 v16, v16, v17
	v_cvt_pk_bf16_f32 v17, v18, v19
	v_cvt_pk_bf16_f32 v20, v20, v21
	v_cvt_pk_bf16_f32 v21, v22, v23
	v_cvt_pk_bf16_f32 v24, v24, v25
	v_cvt_pk_bf16_f32 v25, v26, v27
	v_cvt_pk_bf16_f32 v28, v28, v29
	v_cvt_pk_bf16_f32 v29, v30, v31
	global_store_dwordx2 v8, v[16:17], s[24:25] offset:224
	global_store_dwordx2 v8, v[20:21], s[26:27] offset:224
	global_store_dwordx2 v8, v[24:25], s[28:29] offset:224
	global_store_dwordx2 v8, v[28:29], s[64:65] offset:224
	s_nop 1
	s_waitcnt vmcnt(0) lgkmcnt(0)
	s_barrier
	s_mov_b64 exec, -1
	v_readlane_b32 s0, v247, 1
	v_readlane_b32 s1, v247, 2
	v_readlane_b32 s6, v247, 0
	v_readlane_b32 s16, v248, 25
	s_nop 1
	s_load_dwordx2 s[4:5], s[0:1], 0x20
	s_lshr_b32 s16, s16, 3
	s_mul_i32 s16, s16, 0xc000
	s_lshr_b32 s20, s6, 1
	s_lshl_b32 s20, s20, 6
	s_and_b32 s2, s6, 1
	s_lshl_b32 s2, s2, 9
	s_waitcnt lgkmcnt(0)
	s_add_u32 s4, s4, s16
	s_addc_u32 s5, s5, 0
	s_load_dwordx2 s[8:9], s[0:1], 0xe8
	v_lshrrev_b32_e32 v7, 6, v234
	s_mov_b32 s12, 0xbfb8aa3b
	v_readfirstlane_b32 s11, v7
	s_mov_b32 s13, 0xbfb8aa3b
	s_mov_b32 s14, 1.0
	s_mov_b32 s15, 1.0
	v_lshlrev_b32_e32 v7, 3, v237
	v_add_u32_e32 v7, s2, v7
	v_lshlrev_b32_e32 v0, 1, v7
	v_lshlrev_b32_e32 v3, 2, v7
	v_add_u32_e32 v1, 0x800, v0
	v_add_u32_e32 v2, 0x1000, v0
	v_add_u32_e32 v4, 0x1f100000, v0
	v_add_u32_e32 v5, 0x20100000, v0
	v_add_u32_e32 v6, 0x21100000, v0
	s_lshl_b32 s3, s11, 3
	s_add_u32 s3, s3, s20
	s_add_i32 s10, s3, -3
	s_lshl_b32 s3, s3, 11
	s_waitcnt lgkmcnt(0)
	s_add_u32 s6, s8, s3
	s_addc_u32 s7, s9, 0
	s_mul_i32 s3, s10, 0x7e00
	s_ashr_i32 vcc_lo, s3, 31
	s_add_u32 s100, s8, s3
	s_addc_u32 s101, s9, vcc_lo
	s_add_u32 s100, s100, 0x9c00000
	s_addc_u32 s101, s101, 0
	global_load_dwordx4 v[96:99], v3, s[4:5]
	global_load_dwordx4 v[100:103], v3, s[4:5] offset:16
	s_add_u32 vcc_lo, s4, 0x3000
	s_addc_u32 vcc_hi, s5, 0
	global_load_dwordx4 v[104:107], v3, vcc
	global_load_dwordx4 v[108:111], v3, vcc offset:16
	s_add_u32 vcc_lo, s4, 0x6000
	s_addc_u32 vcc_hi, s5, 0
	global_load_dwordx4 v[112:115], v3, vcc
	global_load_dwordx4 v[116:119], v3, vcc offset:16
	s_add_u32 vcc_lo, s4, 0x9000
	s_addc_u32 vcc_hi, s5, 0
	global_load_dwordx4 v[120:123], v3, vcc
	global_load_dwordx4 v[124:127], v3, vcc offset:16
	global_load_dwordx4 v[52:55], v0, s[100:101]
	s_add_u32 s100, s100, 0x7e00
	s_addc_u32 s101, s101, 0
	global_load_dwordx4 v[56:59], v0, s[100:101]
	s_add_u32 s100, s100, 0x7e00
	s_addc_u32 s101, s101, 0
	global_load_dwordx4 v[60:63], v0, s[100:101]
	s_add_u32 s100, s100, 0x7e00
	s_addc_u32 s101, s101, 0
	global_load_dwordx4 v[64:67], v0, s[100:101]
	s_add_u32 s100, s100, 0x7e00
	s_addc_u32 s101, s101, 0
	global_load_dwordx4 v[68:71], v0, s[100:101]
	s_add_u32 s100, s100, 0x7e00
	s_addc_u32 s101, s101, 0
	global_load_dwordx4 v[72:75], v0, s[100:101]
	s_add_u32 s100, s100, 0x7e00
	s_addc_u32 s101, s101, 0
	global_load_dwordx4 v[76:79], v0, s[100:101]
	s_add_u32 s100, s100, 0x7e00
	s_addc_u32 s101, s101, 0
	global_load_dwordx4 v[80:83], v0, s[100:101]
	s_add_u32 s100, s100, 0x7e00
	s_addc_u32 s101, s101, 0
	global_load_dwordx4 v[84:87], v0, s[100:101]
	s_add_u32 s100, s100, 0x7e00
	s_addc_u32 s101, s101, 0
	global_load_dwordx4 v[88:91], v0, s[100:101]
	s_add_u32 s100, s100, 0x7e00
	s_addc_u32 s101, s101, 0
	global_load_dwordx4 v[92:95], v0, s[100:101]
	s_sub_u32 s100, s100, 0x4ec00
	s_subb_u32 s101, s101, 0
	s_add_u32 vcc_lo, s4, 0x1000
	s_addc_u32 vcc_hi, s5, 0
	global_load_dwordx4 v[8:11], v3, vcc
	global_load_dwordx4 v[12:15], v3, vcc offset:16
	s_add_u32 vcc_lo, s4, 0x4000
	s_addc_u32 vcc_hi, s5, 0
	global_load_dwordx4 v[16:19], v3, vcc
	global_load_dwordx4 v[20:23], v3, vcc offset:16
	s_add_u32 vcc_lo, s4, 0x7000
	s_addc_u32 vcc_hi, s5, 0
	global_load_dwordx4 v[24:27], v3, vcc
	global_load_dwordx4 v[28:31], v3, vcc offset:16
	s_add_u32 vcc_lo, s4, 0xa000
	s_addc_u32 vcc_hi, s5, 0
	global_load_dwordx4 v[32:35], v3, vcc
	global_load_dwordx4 v[36:39], v3, vcc offset:16
	s_waitcnt vmcnt(16)
	s_cmp_lt_i32 s10, 0
	s_cbranch_scc0 .Ldnc_nz0
	v_mov_b32_e32 v52, 0
	v_mov_b32_e32 v53, 0
	v_mov_b32_e32 v54, 0
	v_mov_b32_e32 v55, 0
	v_mov_b32_e32 v56, 0
	v_mov_b32_e32 v57, 0
	v_mov_b32_e32 v58, 0
	v_mov_b32_e32 v59, 0
	v_mov_b32_e32 v60, 0
	v_mov_b32_e32 v61, 0
	v_mov_b32_e32 v62, 0
	v_mov_b32_e32 v63, 0

; __device__ __forceinline__ unsigned pk2(float lo, float hi) { const f32v2_t v = {lo, hi}; const bf16v2_t b = __builtin_convertvector(v, bf16v2_t); return __builtin_bit_cast(unsigned, b); }
; __device__ __forceinline__ float lo16(unsigned u) { return __uint_as_float(u << 16); }
; __device__ __forceinline__ float hi16(unsigned u) { return __uint_as_float(u & 0xffff0000u); }
; __device__ __forceinline__ float siluf_(float x) { return x * __builtin_amdgcn_rcpf(1.0f + __expf(-x)); }
; __device__ __forceinline__ void prep_dn_finish(const float* cw, bf16_t* dq, bf16_t* dk, bf16_t* dv, const u32x4 (&raw)[4], int t, int ch) {
;     float a[8];
; #pragma unroll
;     for (int e = 0; e < 8; ++e) a[e] = 0.f;
; #pragma unroll
;     for (int k = 0; k < 4; ++k) {
;         const f32x4 w0 = *(const f32x4*)(cw + k * 3072 + ch), w1 = *(const f32x4*)(cw + k * 3072 + ch + 4);
;         a[0] += w0[0] * lo16(raw[k].x); a[1] += w0[1] * hi16(raw[k].x); a[2] += w0[2] * lo16(raw[k].y); a[3] += w0[3] * hi16(raw[k].y);
;         a[4] += w1[0] * lo16(raw[k].z); a[5] += w1[1] * hi16(raw[k].z); a[6] += w1[2] * lo16(raw[k].w); a[7] += w1[3] * hi16(raw[k].w); }
;     float ss = 0.f;
; #pragma unroll
;     for (int e = 0; e < 8; ++e) { a[e] = siluf_(a[e]); ss += a[e] * a[e]; }
;     ss += __shfl_xor(ss, 1); ss += __shfl_xor(ss, 2); ss += __shfl_xor(ss, 4); ss += __shfl_xor(ss, 8);
;     float sc = 1.0f;
;     if (ch < 2048) { sc = rsqrtf(ss + EPS); if (ch < 1024) sc *= 0.08838834764831845f; }
;     u32x4 w; w.x = pk2(a[0] * sc, a[1] * sc); w.y = pk2(a[2] * sc, a[3] * sc); w.z = pk2(a[4] * sc, a[5] * sc); w.w = pk2(a[6] * sc, a[7] * sc);
;     bf16_t* dst = (ch < 1024) ? dq : (ch < 2048 ? dk : dv);
;     *(u32x4*)(dst + (size_t)t * 1024 + (ch & 1023)) = w;
.Ldnc_nz2:
	v_lshlrev_b32_e32 v128, 16, v52
	v_and_b32_e32 v129, 0xffff0000, v52
	v_lshlrev_b32_e32 v130, 16, v53
	v_and_b32_e32 v131, 0xffff0000, v53
	v_lshlrev_b32_e32 v132, 16, v54
	v_and_b32_e32 v133, 0xffff0000, v54
	v_lshlrev_b32_e32 v134, 16, v55
	v_and_b32_e32 v135, 0xffff0000, v55
	v_lshlrev_b32_e32 v136, 16, v56
	v_and_b32_e32 v137, 0xffff0000, v56
	v_lshlrev_b32_e32 v138, 16, v57
	v_and_b32_e32 v139, 0xffff0000, v57
	v_lshlrev_b32_e32 v140, 16, v58
	v_and_b32_e32 v141, 0xffff0000, v58
	v_lshlrev_b32_e32 v142, 16, v59
	v_and_b32_e32 v143, 0xffff0000, v59
	v_lshlrev_b32_e32 v146, 16, v60
	v_and_b32_e32 v147, 0xffff0000, v60
	v_lshlrev_b32_e32 v148, 16, v61
	v_and_b32_e32 v149, 0xffff0000, v61
	v_lshlrev_b32_e32 v150, 16, v62
	v_and_b32_e32 v151, 0xffff0000, v62
	v_lshlrev_b32_e32 v152, 16, v63
	v_and_b32_e32 v153, 0xffff0000, v63
	s_waitcnt vmcnt(15)
	v_lshlrev_b32_e32 v154, 16, v64
	v_and_b32_e32 v155, 0xffff0000, v64
	v_lshlrev_b32_e32 v156, 16, v65
	v_and_b32_e32 v157, 0xffff0000, v65
	v_lshlrev_b32_e32 v158, 16, v66
	v_and_b32_e32 v159, 0xffff0000, v66
	v_lshlrev_b32_e32 v160, 16, v67
	v_and_b32_e32 v161, 0xffff0000, v67
	v_pk_mul_f32 v[162:163], v[96:97], v[128:129]
	v_pk_mul_f32 v[164:165], v[98:99], v[130:131]
	v_pk_mul_f32 v[166:167], v[100:101], v[132:133]
	v_pk_mul_f32 v[168:169], v[102:103], v[134:135]
	v_pk_fma_f32 v[162:163], v[104:105], v[136:137], v[162:163]
	v_pk_fma_f32 v[164:165], v[106:107], v[138:139], v[164:165]
	v_pk_fma_f32 v[166:167], v[108:109], v[140:141], v[166:167]
	v_pk_fma_f32 v[168:169], v[110:111], v[142:143], v[168:169]
	v_pk_fma_f32 v[162:163], v[112:113], v[146:147], v[162:163]
	v_pk_fma_f32 v[164:165], v[114:115], v[148:149], v[164:165]
	v_pk_fma_f32 v[166:167], v[116:117], v[150:151], v[166:167]
	v_pk_fma_f32 v[168:169], v[118:119], v[152:153], v[168:169]
	v_pk_fma_f32 v[162:163], v[120:121], v[154:155], v[162:163]
	v_pk_fma_f32 v[164:165], v[122:123], v[156:157], v[164:165]
	v_pk_fma_f32 v[166:167], v[124:125], v[158:159], v[166:167]
	v_pk_fma_f32 v[168:169], v[126:127], v[160:161], v[168:169]
	v_pk_mul_f32 v[40:41], v[162:163], s[12:13]
	v_pk_mul_f32 v[42:43], v[164:165], s[12:13]
	v_pk_mul_f32 v[44:45], v[166:167], s[12:13]
	v_pk_mul_f32 v[46:47], v[168:169], s[12:13]
	v_exp_f32_e32 v40, v40
	v_exp_f32_e32 v41, v41
	v_exp_f32_e32 v42, v42
	v_exp_f32_e32 v43, v43
	v_exp_f32_e32 v44, v44
	v_exp_f32_e32 v45, v45
	v_exp_f32_e32 v46, v46
	v_exp_f32_e32 v47, v47
	v_pk_add_f32 v[40:41], v[40:41], s[14:15]
	v_pk_add_f32 v[42:43], v[42:43], s[14:15]
	v_pk_add_f32 v[44:45], v[44:45], s[14:15]
	v_pk_add_f32 v[46:47], v[46:47], s[14:15]
	v_rcp_f32_e32 v40, v40
	v_rcp_f32_e32 v41, v41
	v_rcp_f32_e32 v42, v42
	v_rcp_f32_e32 v43, v43
	v_rcp_f32_e32 v44, v44
	v_rcp_f32_e32 v45, v45
	v_rcp_f32_e32 v46, v46
	v_rcp_f32_e32 v47, v47
	v_pk_mul_f32 v[162:163], v[162:163], v[40:41]
	v_pk_mul_f32 v[164:165], v[164:165], v[42:43]
	v_pk_mul_f32 v[166:167], v[166:167], v[44:45]
	v_pk_mul_f32 v[168:169], v[168:169], v[46:47]
	v_cvt_pk_bf16_f32 v170, v162, v163
	v_cvt_pk_bf16_f32 v171, v164, v165
	v_cvt_pk_bf16_f32 v172, v166, v167
	v_cvt_pk_bf16_f32 v173, v168, v169
	global_store_dwordx4 v6, v[170:173], s[6:7]
	s_add_u32 s6, s6, 0x800
	s_addc_u32 s7, s7, 0
	s_waitcnt vmcnt(14)
	v_lshlrev_b32_e32 v128, 16, v68
	v_and_b32_e32 v129, 0xffff0000, v68
	v_lshlrev_b32_e32 v130, 16, v69
	v_and_b32_e32 v131, 0xffff0000, v69
	v_lshlrev_b32_e32 v132, 16, v70
	v_and_b32_e32 v133, 0xffff0000, v70
	v_lshlrev_b32_e32 v134, 16, v71
	v_and_b32_e32 v135, 0xffff0000, v71
	v_pk_mul_f32 v[162:163], v[96:97], v[136:137]
	v_pk_mul_f32 v[164:165], v[98:99], v[138:139]
	v_pk_mul_f32 v[166:167], v[100:101], v[140:141]
	v_pk_mul_f32 v[168:169], v[102:103], v[142:143]
	v_pk_fma_f32 v[162:163], v[104:105], v[146:147], v[162:163]
	v_pk_fma_f32 v[164:165], v[106:107], v[148:149], v[164:165]
	v_pk_fma_f32 v[166:167], v[108:109], v[150:151], v[166:167]
	v_pk_fma_f32 v[168:169], v[110:111], v[152:153], v[168:169]
	v_pk_fma_f32 v[162:163], v[112:113], v[154:155], v[162:163]
	v_pk_fma_f32 v[164:165], v[114:115], v[156:157], v[164:165]
	v_pk_fma_f32 v[166:167], v[116:117], v[158:159], v[166:167]
	v_pk_fma_f32 v[168:169], v[118:119], v[160:161], v[168:169]
	v_pk_fma_f32 v[162:163], v[120:121], v[128:129], v[162:163]
	v_pk_fma_f32 v[164:165], v[122:123], v[130:131], v[164:165]
	v_pk_fma_f32 v[166:167], v[124:125], v[132:133], v[166:167]
	v_pk_fma_f32 v[168:169], v[126:127], v[134:135], v[168:169]
	v_pk_mul_f32 v[40:41], v[162:163], s[12:13]
	v_pk_mul_f32 v[42:43], v[164:165], s[12:13]
	v_pk_mul_f32 v[44:45], v[166:167], s[12:13]
	v_pk_mul_f32 v[46:47], v[168:169], s[12:13]
	v_exp_f32_e32 v40, v40
	v_exp_f32_e32 v41, v41
	v_exp_f32_e32 v42, v42
	v_exp_f32_e32 v43, v43
	v_exp_f32_e32 v44, v44
	v_exp_f32_e32 v45, v45
	v_exp_f32_e32 v46, v46
	v_exp_f32_e32 v47, v47
	v_pk_add_f32 v[40:41], v[40:41], s[14:15]
	v_pk_add_f32 v[42:43], v[42:43], s[14:15]
	v_pk_add_f32 v[44:45], v[44:45], s[14:15]
	v_pk_add_f32 v[46:47], v[46:47], s[14:15]
	v_rcp_f32_e32 v40, v40
	v_rcp_f32_e32 v41, v41
	v_rcp_f32_e32 v42, v42
	v_rcp_f32_e32 v43, v43
	v_rcp_f32_e32 v44, v44
	v_rcp_f32_e32 v45, v45
	v_rcp_f32_e32 v46, v46
	v_rcp_f32_e32 v47, v47
	v_pk_mul_f32 v[162:163], v[162:163], v[40:41]
	v_pk_mul_f32 v[164:165], v[164:165], v[42:43]
	v_pk_mul_f32 v[166:167], v[166:167], v[44:45]
	v_pk_mul_f32 v[168:169], v[168:169], v[46:47]
	v_cvt_pk_bf16_f32 v170, v162, v163
	v_cvt_pk_bf16_f32 v171, v164, v165
	v_cvt_pk_bf16_f32 v172, v166, v167
	v_cvt_pk_bf16_f32 v173, v168, v169
	global_store_dwordx4 v6, v[170:173], s[6:7]
	s_add_u32 s6, s6, 0x800
	s_addc_u32 s7, s7, 0
	s_waitcnt vmcnt(13)
; __device__ __forceinline__ unsigned pk2(float lo, float hi) { const f32v2_t v = {lo, hi}; const bf16v2_t b = __builtin_convertvector(v, bf16v2_t); return __builtin_bit_cast(unsigned, b); }
; __device__ __forceinline__ float lo16(unsigned u) { return __uint_as_float(u << 16); }
; __device__ __forceinline__ float hi16(unsigned u) { return __uint_as_float(u & 0xffff0000u); }
; __device__ __forceinline__ float siluf_(float x) { return x * __builtin_amdgcn_rcpf(1.0f + __expf(-x)); }
; __device__ __forceinline__ void prep_dn_finish(const float* cw, bf16_t* dq, bf16_t* dk, bf16_t* dv, const u32x4 (&raw)[4], int t, int ch) {
;     ...
;     for (int k = 0; k < 4; ++k) {
;         const f32x4 w0 = *(const f32x4*)(cw + k * 3072 + ch), w1 = *(const f32x4*)(cw + k * 3072 + ch + 4);
;         a[0] += w0[0] * lo16(raw[k].x); a[1] += w0[1] * hi16(raw[k].x); a[2] += w0[2] * lo16(raw[k].y); a[3] += w0[3] * hi16(raw[k].y);
;         a[4] += w1[0] * lo16(raw[k].z); a[5] += w1[1] * hi16(raw[k].z); a[6] += w1[2] * lo16(raw[k].w); a[7] += w1[3] * hi16(raw[k].w); }
;     float ss = 0.f;
; #pragma unroll
;     for (int e = 0; e < 8; ++e) { a[e] = siluf_(a[e]); ss += a[e] * a[e]; }
;     ss += __shfl_xor(ss, 1); ss += __shfl_xor(ss, 2); ss += __shfl_xor(ss, 4); ss += __shfl_xor(ss, 8);
;     float sc = 1.0f;
;     if (ch < 2048) { sc = rsqrtf(ss + EPS); if (ch < 1024) sc *= 0.08838834764831845f; }
;     u32x4 w; w.x = pk2(a[0] * sc, a[1] * sc); w.y = pk2(a[2] * sc, a[3] * sc); w.z = pk2(a[4] * sc, a[5] * sc); w.w = pk2(a[6] * sc, a[7] * sc);
;     bf16_t* dst = (ch < 1024) ? dq : (ch < 2048 ? dk : dv);
;     *(u32x4*)(dst + (size_t)t * 1024 + (ch & 1023)) = w;
	v_lshlrev_b32_e32 v136, 16, v72
	v_and_b32_e32 v137, 0xffff0000, v72
	v_lshlrev_b32_e32 v138, 16, v73
	v_and_b32_e32 v139, 0xffff0000, v73
	v_lshlrev_b32_e32 v140, 16, v74
	v_and_b32_e32 v141, 0xffff0000, v74
	v_lshlrev_b32_e32 v142, 16, v75
	v_and_b32_e32 v143, 0xffff0000, v75
	v_pk_mul_f32 v[162:163], v[96:97], v[146:147]
	v_pk_mul_f32 v[164:165], v[98:99], v[148:149]
	v_pk_mul_f32 v[166:167], v[100:101], v[150:151]
	v_pk_mul_f32 v[168:169], v[102:103], v[152:153]
	v_pk_fma_f32 v[162:163], v[104:105], v[154:155], v[162:163]
	v_pk_fma_f32 v[164:165], v[106:107], v[156:157], v[164:165]
	v_pk_fma_f32 v[166:167], v[108:109], v[158:159], v[166:167]
	v_pk_fma_f32 v[168:169], v[110:111], v[160:161], v[168:169]
	v_pk_fma_f32 v[162:163], v[112:113], v[128:129], v[162:163]
	v_pk_fma_f32 v[164:165], v[114:115], v[130:131], v[164:165]
	v_pk_fma_f32 v[166:167], v[116:117], v[132:133], v[166:167]
	v_pk_fma_f32 v[168:169], v[118:119], v[134:135], v[168:169]
	v_pk_fma_f32 v[162:163], v[120:121], v[136:137], v[162:163]
	v_pk_fma_f32 v[164:165], v[122:123], v[138:139], v[164:165]
	v_pk_fma_f32 v[166:167], v[124:125], v[140:141], v[166:167]
	v_pk_fma_f32 v[168:169], v[126:127], v[142:143], v[168:169]
	v_pk_mul_f32 v[40:41], v[162:163], s[12:13]
	v_pk_mul_f32 v[42:43], v[164:165], s[12:13]
	v_pk_mul_f32 v[44:45], v[166:167], s[12:13]
	v_pk_mul_f32 v[46:47], v[168:169], s[12:13]
	v_exp_f32_e32 v40, v40
	v_exp_f32_e32 v41, v41
	v_exp_f32_e32 v42, v42
	v_exp_f32_e32 v43, v43
	v_exp_f32_e32 v44, v44
	v_exp_f32_e32 v45, v45
	v_exp_f32_e32 v46, v46
	v_exp_f32_e32 v47, v47
	v_pk_add_f32 v[40:41], v[40:41], s[14:15]
	v_pk_add_f32 v[42:43], v[42:43], s[14:15]
	v_pk_add_f32 v[44:45], v[44:45], s[14:15]
	v_pk_add_f32 v[46:47], v[46:47], s[14:15]
	v_rcp_f32_e32 v40, v40
	v_rcp_f32_e32 v41, v41
	v_rcp_f32_e32 v42, v42
	v_rcp_f32_e32 v43, v43
	v_rcp_f32_e32 v44, v44
	v_rcp_f32_e32 v45, v45
	v_rcp_f32_e32 v46, v46
	v_rcp_f32_e32 v47, v47
	v_pk_mul_f32 v[162:163], v[162:163], v[40:41]
	v_pk_mul_f32 v[164:165], v[164:165], v[42:43]
	v_pk_mul_f32 v[166:167], v[166:167], v[44:45]
	v_pk_mul_f32 v[168:169], v[168:169], v[46:47]
	v_cvt_pk_bf16_f32 v170, v162, v163
	v_cvt_pk_bf16_f32 v171, v164, v165
	v_cvt_pk_bf16_f32 v172, v166, v167
	v_cvt_pk_bf16_f32 v173, v168, v169
	global_store_dwordx4 v6, v[170:173], s[6:7]
	s_add_u32 s6, s6, 0x800
	s_addc_u32 s7, s7, 0
	s_waitcnt vmcnt(12)
	v_lshlrev_b32_e32 v146, 16, v76
	v_and_b32_e32 v147, 0xffff0000, v76
	v_lshlrev_b32_e32 v148, 16, v77
	v_and_b32_e32 v149, 0xffff0000, v77
	v_lshlrev_b32_e32 v150, 16, v78
	v_and_b32_e32 v151, 0xffff0000, v78
	v_lshlrev_b32_e32 v152, 16, v79
	v_and_b32_e32 v153, 0xffff0000, v79
	v_pk_mul_f32 v[162:163], v[96:97], v[154:155]
	v_pk_mul_f32 v[164:165], v[98:99], v[156:157]
	v_pk_mul_f32 v[166:167], v[100:101], v[158:159]
	v_pk_mul_f32 v[168:169], v[102:103], v[160:161]
	v_pk_fma_f32 v[162:163], v[104:105], v[128:129], v[162:163]
	v_pk_fma_f32 v[164:165], v[106:107], v[130:131], v[164:165]
	v_pk_fma_f32 v[166:167], v[108:109], v[132:133], v[166:167]
	v_pk_fma_f32 v[168:169], v[110:111], v[134:135], v[168:169]
	v_pk_fma_f32 v[162:163], v[112:113], v[136:137], v[162:163]
	v_pk_fma_f32 v[164:165], v[114:115], v[138:139], v[164:165]
	v_pk_fma_f32 v[166:167], v[116:117], v[140:141], v[166:167]
	v_pk_fma_f32 v[168:169], v[118:119], v[142:143], v[168:169]
	v_pk_fma_f32 v[162:163], v[120:121], v[146:147], v[162:163]
	v_pk_fma_f32 v[164:165], v[122:123], v[148:149], v[164:165]
	v_pk_fma_f32 v[166:167], v[124:125], v[150:151], v[166:167]
	v_pk_fma_f32 v[168:169], v[126:127], v[152:153], v[168:169]
	v_pk_mul_f32 v[40:41], v[162:163], s[12:13]
	v_pk_mul_f32 v[42:43], v[164:165], s[12:13]
	v_pk_mul_f32 v[44:45], v[166:167], s[12:13]
	v_pk_mul_f32 v[46:47], v[168:169], s[12:13]
	v_exp_f32_e32 v40, v40
	v_exp_f32_e32 v41, v41
	v_exp_f32_e32 v42, v42
	v_exp_f32_e32 v43, v43
	v_exp_f32_e32 v44, v44
	v_exp_f32_e32 v45, v45
	v_exp_f32_e32 v46, v46
	v_exp_f32_e32 v47, v47
	v_pk_add_f32 v[40:41], v[40:41], s[14:15]
	v_pk_add_f32 v[42:43], v[42:43], s[14:15]
	v_pk_add_f32 v[44:45], v[44:45], s[14:15]
	v_pk_add_f32 v[46:47], v[46:47], s[14:15]
	v_rcp_f32_e32 v40, v40
	v_rcp_f32_e32 v41, v41
	v_rcp_f32_e32 v42, v42
	v_rcp_f32_e32 v43, v43
	v_rcp_f32_e32 v44, v44
	v_rcp_f32_e32 v45, v45
	v_rcp_f32_e32 v46, v46
	v_rcp_f32_e32 v47, v47
	v_pk_mul_f32 v[162:163], v[162:163], v[40:41]
	v_pk_mul_f32 v[164:165], v[164:165], v[42:43]
	v_pk_mul_f32 v[166:167], v[166:167], v[44:45]
	v_pk_mul_f32 v[168:169], v[168:169], v[46:47]
	v_cvt_pk_bf16_f32 v170, v162, v163
	v_cvt_pk_bf16_f32 v171, v164, v165
	v_cvt_pk_bf16_f32 v172, v166, v167
	v_cvt_pk_bf16_f32 v173, v168, v169
	global_store_dwordx4 v6, v[170:173], s[6:7]
	s_add_u32 s6, s6, 0x800
	s_addc_u32 s7, s7, 0
	s_waitcnt vmcnt(11)
; __device__ __forceinline__ unsigned pk2(float lo, float hi) { const f32v2_t v = {lo, hi}; const bf16v2_t b = __builtin_convertvector(v, bf16v2_t); return __builtin_bit_cast(unsigned, b); }
; __device__ __forceinline__ float lo16(unsigned u) { return __uint_as_float(u << 16); }
; __device__ __forceinline__ float hi16(unsigned u) { return __uint_as_float(u & 0xffff0000u); }
; __device__ __forceinline__ float siluf_(float x) { return x * __builtin_amdgcn_rcpf(1.0f + __expf(-x)); }
; __device__ __forceinline__ void prep_dn_finish(const float* cw, bf16_t* dq, bf16_t* dk, bf16_t* dv, const u32x4 (&raw)[4], int t, int ch) {
;     ...
;     for (int k = 0; k < 4; ++k) {
;         const f32x4 w0 = *(const f32x4*)(cw + k * 3072 + ch), w1 = *(const f32x4*)(cw + k * 3072 + ch + 4);
;         a[0] += w0[0] * lo16(raw[k].x); a[1] += w0[1] * hi16(raw[k].x); a[2] += w0[2] * lo16(raw[k].y); a[3] += w0[3] * hi16(raw[k].y);
;         a[4] += w1[0] * lo16(raw[k].z); a[5] += w1[1] * hi16(raw[k].z); a[6] += w1[2] * lo16(raw[k].w); a[7] += w1[3] * hi16(raw[k].w); }
;     float ss = 0.f;
; #pragma unroll
;     for (int e = 0; e < 8; ++e) { a[e] = siluf_(a[e]); ss += a[e] * a[e]; }
;     ss += __shfl_xor(ss, 1); ss += __shfl_xor(ss, 2); ss += __shfl_xor(ss, 4); ss += __shfl_xor(ss, 8);
;     float sc = 1.0f;
;     if (ch < 2048) { sc = rsqrtf(ss + EPS); if (ch < 1024) sc *= 0.08838834764831845f; }
;     u32x4 w; w.x = pk2(a[0] * sc, a[1] * sc); w.y = pk2(a[2] * sc, a[3] * sc); w.z = pk2(a[4] * sc, a[5] * sc); w.w = pk2(a[6] * sc, a[7] * sc);
;     bf16_t* dst = (ch < 1024) ? dq : (ch < 2048 ? dk : dv);
;     *(u32x4*)(dst + (size_t)t * 1024 + (ch & 1023)) = w;
	v_lshlrev_b32_e32 v154, 16, v80
	v_and_b32_e32 v155, 0xffff0000, v80
	v_lshlrev_b32_e32 v156, 16, v81
	v_and_b32_e32 v157, 0xffff0000, v81
	v_lshlrev_b32_e32 v158, 16, v82
	v_and_b32_e32 v159, 0xffff0000, v82
	v_lshlrev_b32_e32 v160, 16, v83
	v_and_b32_e32 v161, 0xffff0000, v83
	v_pk_mul_f32 v[162:163], v[96:97], v[128:129]
	v_pk_mul_f32 v[164:165], v[98:99], v[130:131]
	v_pk_mul_f32 v[166:167], v[100:101], v[132:133]
	v_pk_mul_f32 v[168:169], v[102:103], v[134:135]
	v_pk_fma_f32 v[162:163], v[104:105], v[136:137], v[162:163]
	v_pk_fma_f32 v[164:165], v[106:107], v[138:139], v[164:165]
	v_pk_fma_f32 v[166:167], v[108:109], v[140:141], v[166:167]
	v_pk_fma_f32 v[168:169], v[110:111], v[142:143], v[168:169]
	v_pk_fma_f32 v[162:163], v[112:113], v[146:147], v[162:163]
	v_pk_fma_f32 v[164:165], v[114:115], v[148:149], v[164:165]
	v_pk_fma_f32 v[166:167], v[116:117], v[150:151], v[166:167]
	v_pk_fma_f32 v[168:169], v[118:119], v[152:153], v[168:169]
	v_pk_fma_f32 v[162:163], v[120:121], v[154:155], v[162:163]
	v_pk_fma_f32 v[164:165], v[122:123], v[156:157], v[164:165]
	v_pk_fma_f32 v[166:167], v[124:125], v[158:159], v[166:167]
	v_pk_fma_f32 v[168:169], v[126:127], v[160:161], v[168:169]
	v_pk_mul_f32 v[40:41], v[162:163], s[12:13]
	v_pk_mul_f32 v[42:43], v[164:165], s[12:13]
	v_pk_mul_f32 v[44:45], v[166:167], s[12:13]
	v_pk_mul_f32 v[46:47], v[168:169], s[12:13]
	v_exp_f32_e32 v40, v40
	v_exp_f32_e32 v41, v41
	v_exp_f32_e32 v42, v42
	v_exp_f32_e32 v43, v43
	v_exp_f32_e32 v44, v44
	v_exp_f32_e32 v45, v45
	v_exp_f32_e32 v46, v46
	v_exp_f32_e32 v47, v47
	v_pk_add_f32 v[40:41], v[40:41], s[14:15]
	v_pk_add_f32 v[42:43], v[42:43], s[14:15]
	v_pk_add_f32 v[44:45], v[44:45], s[14:15]
	v_pk_add_f32 v[46:47], v[46:47], s[14:15]
	v_rcp_f32_e32 v40, v40
	v_rcp_f32_e32 v41, v41
	v_rcp_f32_e32 v42, v42
	v_rcp_f32_e32 v43, v43
	v_rcp_f32_e32 v44, v44
	v_rcp_f32_e32 v45, v45
	v_rcp_f32_e32 v46, v46
	v_rcp_f32_e32 v47, v47
	v_pk_mul_f32 v[162:163], v[162:163], v[40:41]
	v_pk_mul_f32 v[164:165], v[164:165], v[42:43]
	v_pk_mul_f32 v[166:167], v[166:167], v[44:45]
	v_pk_mul_f32 v[168:169], v[168:169], v[46:47]
	v_cvt_pk_bf16_f32 v170, v162, v163
	v_cvt_pk_bf16_f32 v171, v164, v165
	v_cvt_pk_bf16_f32 v172, v166, v167
	v_cvt_pk_bf16_f32 v173, v168, v169
	global_store_dwordx4 v6, v[170:173], s[6:7]
	s_add_u32 s6, s6, 0x800
	s_addc_u32 s7, s7, 0
	s_waitcnt vmcnt(10)
	v_lshlrev_b32_e32 v128, 16, v84
	v_and_b32_e32 v129, 0xffff0000, v84
	v_lshlrev_b32_e32 v130, 16, v85
	v_and_b32_e32 v131, 0xffff0000, v85
	v_lshlrev_b32_e32 v132, 16, v86
	v_and_b32_e32 v133, 0xffff0000, v86
	v_lshlrev_b32_e32 v134, 16, v87
	v_and_b32_e32 v135, 0xffff0000, v87
	v_pk_mul_f32 v[162:163], v[96:97], v[136:137]
	v_pk_mul_f32 v[164:165], v[98:99], v[138:139]
	v_pk_mul_f32 v[166:167], v[100:101], v[140:141]
	v_pk_mul_f32 v[168:169], v[102:103], v[142:143]
	v_pk_fma_f32 v[162:163], v[104:105], v[146:147], v[162:163]
	v_pk_fma_f32 v[164:165], v[106:107], v[148:149], v[164:165]
	v_pk_fma_f32 v[166:167], v[108:109], v[150:151], v[166:167]
	v_pk_fma_f32 v[168:169], v[110:111], v[152:153], v[168:169]
	v_pk_fma_f32 v[162:163], v[112:113], v[154:155], v[162:163]
	v_pk_fma_f32 v[164:165], v[114:115], v[156:157], v[164:165]
	v_pk_fma_f32 v[166:167], v[116:117], v[158:159], v[166:167]
	v_pk_fma_f32 v[168:169], v[118:119], v[160:161], v[168:169]
	v_pk_fma_f32 v[162:163], v[120:121], v[128:129], v[162:163]
	v_pk_fma_f32 v[164:165], v[122:123], v[130:131], v[164:165]
	v_pk_fma_f32 v[166:167], v[124:125], v[132:133], v[166:167]
	v_pk_fma_f32 v[168:169], v[126:127], v[134:135], v[168:169]
	v_pk_mul_f32 v[40:41], v[162:163], s[12:13]
	v_pk_mul_f32 v[42:43], v[164:165], s[12:13]
	v_pk_mul_f32 v[44:45], v[166:167], s[12:13]
	v_pk_mul_f32 v[46:47], v[168:169], s[12:13]
	v_exp_f32_e32 v40, v40
	v_exp_f32_e32 v41, v41
	v_exp_f32_e32 v42, v42
	v_exp_f32_e32 v43, v43
	v_exp_f32_e32 v44, v44
	v_exp_f32_e32 v45, v45
	v_exp_f32_e32 v46, v46
	v_exp_f32_e32 v47, v47
	v_pk_add_f32 v[40:41], v[40:41], s[14:15]
	v_pk_add_f32 v[42:43], v[42:43], s[14:15]
	v_pk_add_f32 v[44:45], v[44:45], s[14:15]
	v_pk_add_f32 v[46:47], v[46:47], s[14:15]
	v_rcp_f32_e32 v40, v40
	v_rcp_f32_e32 v41, v41
	v_rcp_f32_e32 v42, v42
	v_rcp_f32_e32 v43, v43
	v_rcp_f32_e32 v44, v44
	v_rcp_f32_e32 v45, v45
	v_rcp_f32_e32 v46, v46
	v_rcp_f32_e32 v47, v47
	v_pk_mul_f32 v[162:163], v[162:163], v[40:41]
	v_pk_mul_f32 v[164:165], v[164:165], v[42:43]
	v_pk_mul_f32 v[166:167], v[166:167], v[44:45]
	v_pk_mul_f32 v[168:169], v[168:169], v[46:47]
	v_cvt_pk_bf16_f32 v170, v162, v163
	v_cvt_pk_bf16_f32 v171, v164, v165
	v_cvt_pk_bf16_f32 v172, v166, v167
	v_cvt_pk_bf16_f32 v173, v168, v169
	global_store_dwordx4 v6, v[170:173], s[6:7]
	s_add_u32 s6, s6, 0x800
	s_addc_u32 s7, s7, 0
	s_waitcnt vmcnt(9)
; __device__ __forceinline__ float bf2f(bf16_t b) { return __uint_as_float(((unsigned)b) << 16); }
; __device__ __forceinline__ float lo16(unsigned u) { return __uint_as_float(u << 16); }
; __device__ __forceinline__ void prep_dn_finish(const float* cw, bf16_t* dq, bf16_t* dk, bf16_t* dv, const u32x4 (&raw)[4], int t, int ch) {
;     ...
;     for (int k = 0; k < 4; ++k) {
;         const f32x4 w0 = *(const f32x4*)(cw + k * 3072 + ch), w1 = *(const f32x4*)(cw + k * 3072 + ch + 4);
;         a[0] += w0[0] * lo16(raw[k].x); a[1] += w0[1] * hi16(raw[k].x); a[2] += w0[2] * lo16(raw[k].y); a[3] += w0[3] * hi16(raw[k].y);
;         a[4] += w1[0] * lo16(raw[k].z); a[5] += w1[1] * hi16(raw[k].z); a[6] += w1[2] * lo16(raw[k].w); a[7] += w1[3] * hi16(raw[k].w); }
;     float ss = 0.f;
; #pragma unroll
;     for (int e = 0; e < 8; ++e) { a[e] = siluf_(a[e]); ss += a[e] * a[e]; }
;     ss += __shfl_xor(ss, 1); ss += __shfl_xor(ss, 2); ss += __shfl_xor(ss, 4); ss += __shfl_xor(ss, 8);
;     float sc = 1.0f;
;     if (ch < 2048) { sc = rsqrtf(ss + EPS); if (ch < 1024) sc *= 0.08838834764831845f; }
;     u32x4 w; w.x = pk2(a[0] * sc, a[1] * sc); w.y = pk2(a[2] * sc, a[3] * sc); w.z = pk2(a[4] * sc, a[5] * sc); w.w = pk2(a[6] * sc, a[7] * sc);
;     bf16_t* dst = (ch < 1024) ? dq : (ch < 2048 ? dk : dv);
;     *(u32x4*)(dst + (size_t)t * 1024 + (ch & 1023)) = w;
; __device__ void dn_d1(const Ctx& c, int ip) {
;     const bf16_t* proj = c.W<bf16_t>(WS_PROJ);
;     const bf16_t* dq = c.W<bf16_t>(WS_DQ); const bf16_t* dk = c.W<bf16_t>(WS_DK); const bf16_t* dv = c.W<bf16_t>(WS_DV);
;     const int tid = c.tid, half = tid >> 8, lt = tid & 255, lw = c.wave & 3, r = c.r, q = c.q;
;     const int item = ip * 2 + half, ck = item >> 3, h = item & 7, t0 = ck * 64;
;     float* Ms = c.ldsf + half * (64 * 68 + 128); float* beta_s = Ms + 64 * 68; float* gc_s = beta_s + 64;
;     const size_t ch = (size_t)(ck * 8 + h);
;     __syncthreads();
;     if (lt < 64) { const size_t rb = (size_t)(t0 + lt) * NP;
;         beta_s[lt] = sigmoidf_(bf2f(proj[rb + C_DNB + h]));
;         float g = -__expf(c.in(I_DNALOG)[c.layer * 8 + h]) * softplusf_(bf2f(proj[rb + C_DNA + h]) + c.in(I_DNDTB)[c.layer * 8 + h]);
; #pragma unroll
;         for (int d = 1; d < 64; d <<= 1) { const float o = __shfl_up(g, d); if ((lt & 63) >= d) g += o; }
;         gc_s[lt] = g; }
;     __syncthreads();
	v_lshlrev_b32_e32 v136, 16, v88
	v_and_b32_e32 v137, 0xffff0000, v88
	v_lshlrev_b32_e32 v138, 16, v89
	v_and_b32_e32 v139, 0xffff0000, v89
	v_lshlrev_b32_e32 v140, 16, v90
	v_and_b32_e32 v141, 0xffff0000, v90
	v_lshlrev_b32_e32 v142, 16, v91
	v_and_b32_e32 v143, 0xffff0000, v91
	v_pk_mul_f32 v[162:163], v[96:97], v[146:147]
	v_pk_mul_f32 v[164:165], v[98:99], v[148:149]
	v_pk_mul_f32 v[166:167], v[100:101], v[150:151]
	v_pk_mul_f32 v[168:169], v[102:103], v[152:153]
	v_pk_fma_f32 v[162:163], v[104:105], v[154:155], v[162:163]
	v_pk_fma_f32 v[164:165], v[106:107], v[156:157], v[164:165]
	v_pk_fma_f32 v[166:167], v[108:109], v[158:159], v[166:167]
	v_pk_fma_f32 v[168:169], v[110:111], v[160:161], v[168:169]
	v_pk_fma_f32 v[162:163], v[112:113], v[128:129], v[162:163]
	v_pk_fma_f32 v[164:165], v[114:115], v[130:131], v[164:165]
	v_pk_fma_f32 v[166:167], v[116:117], v[132:133], v[166:167]
	v_pk_fma_f32 v[168:169], v[118:119], v[134:135], v[168:169]
	v_pk_fma_f32 v[162:163], v[120:121], v[136:137], v[162:163]
	v_pk_fma_f32 v[164:165], v[122:123], v[138:139], v[164:165]
	v_pk_fma_f32 v[166:167], v[124:125], v[140:141], v[166:167]
	v_pk_fma_f32 v[168:169], v[126:127], v[142:143], v[168:169]
	v_pk_mul_f32 v[40:41], v[162:163], s[12:13]
	v_pk_mul_f32 v[42:43], v[164:165], s[12:13]
	v_pk_mul_f32 v[44:45], v[166:167], s[12:13]
	v_pk_mul_f32 v[46:47], v[168:169], s[12:13]
	v_exp_f32_e32 v40, v40
	v_exp_f32_e32 v41, v41
	v_exp_f32_e32 v42, v42
	v_exp_f32_e32 v43, v43
	v_exp_f32_e32 v44, v44
	v_exp_f32_e32 v45, v45
	v_exp_f32_e32 v46, v46
	v_exp_f32_e32 v47, v47
	v_pk_add_f32 v[40:41], v[40:41], s[14:15]
	v_pk_add_f32 v[42:43], v[42:43], s[14:15]
	v_pk_add_f32 v[44:45], v[44:45], s[14:15]
	v_pk_add_f32 v[46:47], v[46:47], s[14:15]
	v_rcp_f32_e32 v40, v40
	v_rcp_f32_e32 v41, v41
	v_rcp_f32_e32 v42, v42
	v_rcp_f32_e32 v43, v43
	v_rcp_f32_e32 v44, v44
	v_rcp_f32_e32 v45, v45
	v_rcp_f32_e32 v46, v46
	v_rcp_f32_e32 v47, v47
	v_pk_mul_f32 v[162:163], v[162:163], v[40:41]
	v_pk_mul_f32 v[164:165], v[164:165], v[42:43]
	v_pk_mul_f32 v[166:167], v[166:167], v[44:45]
	v_pk_mul_f32 v[168:169], v[168:169], v[46:47]
	v_cvt_pk_bf16_f32 v170, v162, v163
	v_cvt_pk_bf16_f32 v171, v164, v165
	v_cvt_pk_bf16_f32 v172, v166, v167
	v_cvt_pk_bf16_f32 v173, v168, v169
	global_store_dwordx4 v6, v[170:173], s[6:7]
	s_add_u32 s6, s6, 0x800
	s_addc_u32 s7, s7, 0
	s_waitcnt vmcnt(8)
	v_lshlrev_b32_e32 v146, 16, v92
	v_and_b32_e32 v147, 0xffff0000, v92
	v_lshlrev_b32_e32 v148, 16, v93
	v_and_b32_e32 v149, 0xffff0000, v93
	v_lshlrev_b32_e32 v150, 16, v94
	v_and_b32_e32 v151, 0xffff0000, v94
	v_lshlrev_b32_e32 v152, 16, v95
	v_and_b32_e32 v153, 0xffff0000, v95
	v_pk_mul_f32 v[162:163], v[96:97], v[154:155]
	v_pk_mul_f32 v[164:165], v[98:99], v[156:157]
	v_pk_mul_f32 v[166:167], v[100:101], v[158:159]
	v_pk_mul_f32 v[168:169], v[102:103], v[160:161]
	v_pk_fma_f32 v[162:163], v[104:105], v[128:129], v[162:163]
	v_pk_fma_f32 v[164:165], v[106:107], v[130:131], v[164:165]
	v_pk_fma_f32 v[166:167], v[108:109], v[132:133], v[166:167]
	v_pk_fma_f32 v[168:169], v[110:111], v[134:135], v[168:169]
	v_pk_fma_f32 v[162:163], v[112:113], v[136:137], v[162:163]
	v_pk_fma_f32 v[164:165], v[114:115], v[138:139], v[164:165]
	v_pk_fma_f32 v[166:167], v[116:117], v[140:141], v[166:167]
	v_pk_fma_f32 v[168:169], v[118:119], v[142:143], v[168:169]
	v_pk_fma_f32 v[162:163], v[120:121], v[146:147], v[162:163]
	v_pk_fma_f32 v[164:165], v[122:123], v[148:149], v[164:165]
	v_pk_fma_f32 v[166:167], v[124:125], v[150:151], v[166:167]
	v_pk_fma_f32 v[168:169], v[126:127], v[152:153], v[168:169]
	v_pk_mul_f32 v[40:41], v[162:163], s[12:13]
	v_pk_mul_f32 v[42:43], v[164:165], s[12:13]
	v_pk_mul_f32 v[44:45], v[166:167], s[12:13]
	v_pk_mul_f32 v[46:47], v[168:169], s[12:13]
	v_exp_f32_e32 v40, v40
	v_exp_f32_e32 v41, v41
	v_exp_f32_e32 v42, v42
	v_exp_f32_e32 v43, v43
	v_exp_f32_e32 v44, v44
	v_exp_f32_e32 v45, v45
	v_exp_f32_e32 v46, v46
	v_exp_f32_e32 v47, v47
	v_pk_add_f32 v[40:41], v[40:41], s[14:15]
	v_pk_add_f32 v[42:43], v[42:43], s[14:15]
	v_pk_add_f32 v[44:45], v[44:45], s[14:15]
	v_pk_add_f32 v[46:47], v[46:47], s[14:15]
	v_rcp_f32_e32 v40, v40
	v_rcp_f32_e32 v41, v41
	v_rcp_f32_e32 v42, v42
	v_rcp_f32_e32 v43, v43
	v_rcp_f32_e32 v44, v44
	v_rcp_f32_e32 v45, v45
	v_rcp_f32_e32 v46, v46
	v_rcp_f32_e32 v47, v47
	v_pk_mul_f32 v[162:163], v[162:163], v[40:41]
	v_pk_mul_f32 v[164:165], v[164:165], v[42:43]
	v_pk_mul_f32 v[166:167], v[166:167], v[44:45]
	v_pk_mul_f32 v[168:169], v[168:169], v[46:47]
	v_cvt_pk_bf16_f32 v170, v162, v163
	v_cvt_pk_bf16_f32 v171, v164, v165
	v_cvt_pk_bf16_f32 v172, v166, v167
	v_cvt_pk_bf16_f32 v173, v168, v169
	global_store_dwordx4 v6, v[170:173], s[6:7]
	s_sub_u32 s6, s6, 0x3800
	s_subb_u32 s7, s7, 0
	s_mov_b64 s[6:7], exec
.Ldnd_entry:
	s_mov_b64 exec, -1
	v_readlane_b32 s0, v247, 1
	v_readlane_b32 s1, v247, 2
	v_readlane_b32 s6, v247, 0
	v_readlane_b32 s16, v248, 25
	v_readfirstlane_b32 s9, v234
	s_load_dwordx2 s[4:5], s[0:1], 0xe8
	s_load_dwordx4 s[32:35], s[0:1], 0x28
	s_lshr_b32 s16, s16, 3
	s_lshr_b32 s9, s9, 6
	s_lshr_b32 s7, s6, 1
	s_and_b32 s8, s6, 1
	s_and_b32 s10, s9, 3
	s_lshr_b32 s11, s9, 2
	s_lshl_b32 s15, s7, 6
	s_mul_i32 s24, s11, 0xd000
	v_and_b32_e32 v0, 0xff, v234
	v_and_b32_e32 v3, 63, v234
	v_and_b32_e32 v1, 15, v234
	v_bfe_u32 v2, v234, 4, 2
	s_mov_b32 s12, 0
	s_waitcnt lgkmcnt(0)

; __device__ __forceinline__ unsigned pk2(float lo, float hi) { const f32v2_t v = {lo, hi}; const bf16v2_t b = __builtin_convertvector(v, bf16v2_t); return __builtin_bit_cast(unsigned, b); }
;     template <class Tp> __device__ __forceinline__ Tp* W(size_t off) const { return (Tp*)(ws + off); }
; __device__ void dn_d1(const Ctx& c, int ip) {
;     ...
;     if (isw) { bf16_t* dW = c.W<bf16_t>(WS_DW);
; #pragma unroll
;         for (int i = 0; i < 64; ++i) dW[(ch * 64 + i) * 128 + col] = f2bf(x[i]);
;     } else { bf16_t* dUT = c.W<bf16_t>(WS_DUT);
; #pragma unroll
;         for (int l0 = 0; l0 < 64; l0 += 8) { u32x4 a; a.x = pk2(x[l0], x[l0 + 1]); a.y = pk2(x[l0 + 2], x[l0 + 3]); a.z = pk2(x[l0 + 4], x[l0 + 5]); a.w = pk2(x[l0 + 6], x[l0 + 7]);
;             *(u32x4*)(dUT + (ch * 128 + col) * 64 + l0) = a; } }
.Ldnd_wsync:
	s_waitcnt lgkmcnt(0)
	s_barrier
	ds_read_b128 v[16:19], v6 offset:17408
	ds_read_b128 v[20:23], v6 offset:21760
	ds_read_b128 v[24:27], v6 offset:26112
	ds_read_b128 v[28:31], v6 offset:30464
	s_waitcnt lgkmcnt(0)
	v_add_u32_e32 v12, 0x22100000, v7
	global_store_dwordx4 v12, v[16:19], s[4:5]
	v_add_u32_e32 v12, 0x22101000, v7
	global_store_dwordx4 v12, v[20:23], s[4:5]
	v_add_u32_e32 v12, 0x22102000, v7
	global_store_dwordx4 v12, v[24:27], s[4:5]
	v_add_u32_e32 v12, 0x22103000, v7
	global_store_dwordx4 v12, v[28:31], s[4:5]
	s_add_u32 s12, s12, 1
	s_cmp_lt_u32 s12, 2
	s_cbranch_scc1 .Ldnd_call
	s_waitcnt vmcnt(0) lgkmcnt(0)
	s_barrier
	s_branch .Lmy_tail_exit
